# attention: row-max exchange across quads via v_permlane16/32_swap + v_max instead of ds_bpermute (24 sites in the two inner loops)
# speedup vs baseline: 1.0048x; 1.0048x over previous
; __device__ __forceinline__ void attn_step(int ks, const KVB& b, int L16, int r, int i0, int iq, int lane,
;                                           const bf16x8* qs, f32x4 (&o)[4], float& mrun, float& lrun) {
;   asm volatile("" : "+v"(lane), "+v"(iq));
;   asm volatile("" : "+s"(r), "+s"(i0));
;   const int quad = lane >> 4;
;   bf16x8 qB0 = qs[0], qB1 = qs[64];
;   int cV, sV; attn_desc(ks, quad, r, i0, cV, sV);
;   int D = ks < 12 ? 4 : (ks < 18 ? 16 : 64);
;   f32x4 z = {0.f, 0.f, 0.f, 0.f};
;   f32x4 sa = __builtin_amdgcn_mfma_f32_16x16x32_bf16(b.k0, qB0, z, 0, 0, 0);
;   sa = __builtin_amdgcn_mfma_f32_16x16x32_bf16(b.k1, qB1, sa, 0, 0, 0);
;   f32x4 sb = __builtin_amdgcn_mfma_f32_16x16x32_bf16(b.k2, qB0, z, 0, 0, 0);
;   sb = __builtin_amdgcn_mfma_f32_16x16x32_bf16(b.k3, qB1, sb, 0, 0, 0);
;   int jlo = max(iq - D + (cV < r ? 1 : 0), 0) - sV;
;   int jhi = min(iq + D - (cV > r ? 1 : 0), L16 - 1) - sV;
;   const float NINF = -__builtin_inff();
;   float s8[8];
;   float mt = -1e30f;
; #pragma unroll
;   for (int j = 0; j < 8; ++j) {
;     float sv = j < 4 ? sa[j] : sb[j - 4];
;     sv = (j >= jlo && j <= jhi) ? sv : NINF;
;     s8[j] = sv;
;     mt = fmaxf(mt, sv);
;   }
;   mt = fmaxf(mt, __shfl_xor(mt, 16));
;   mt = fmaxf(mt, __shfl_xor(mt, 32));
;   float mnew = fmaxf(mrun, mt);
;   float alpha = __builtin_amdgcn_exp2f(mrun - mnew);
;   mrun = mnew;
;   float ps = 0.f;
;   float p8[8];
; #pragma unroll
;   for (int j = 0; j < 8; ++j) { p8[j] = __builtin_amdgcn_exp2f(s8[j] - mnew); ps += p8[j]; }
.LBB0_232:
	v_mov_b32_e32 v132, v226
	v_mov_b32_e32 v140, v225
	s_mov_b32 s22, s42
	s_mov_b32 s23, s46
	ds_read_b128 v[128:131], v228
	s_add_i32 s0, s59, -12
	s_and_b32 s20, s0, 8
	s_add_i32 s0, s58, -4
	s_and_b32 s63, s0, 24
	s_add_i32 s63, s63, -4
	v_ashrrev_i32_e32 v141, 4, v132
	ds_read_b128 v[132:135], v228 offset:1024
	s_cmp_lt_u32 s60, 12
	s_waitcnt vmcnt(23) lgkmcnt(1)
	v_mfma_f32_16x16x32_bf16 v[136:139], v[124:127], v[128:131], 0
	v_add_u32_e32 v142, s20, v141
	v_lshlrev_b32_e32 v141, 2, v141
	s_cselect_b64 s[0:1], -1, 0
	s_waitcnt vmcnt(21)
	v_mfma_f32_16x16x32_bf16 v[128:131], v[116:119], v[128:131], 0
	v_and_or_b32 v141, s22, 3, v141
	s_and_b64 s[4:5], s[0:1], exec
	v_cndmask_b32_e64 v141, v141, v142, s[0:1]
	s_cselect_b32 s64, -4, -16
	s_cselect_b32 s61, 4, 16
	s_waitcnt lgkmcnt(0)
	v_mfma_f32_16x16x32_bf16 v[136:139], v[120:123], v[132:135], v[136:139]
	v_mov_b32_e32 v144, s64
	v_cmp_gt_i32_e32 vcc, s22, v141
	v_cmp_lt_i32_e64 s[4:5], s22, v141
	s_waitcnt vmcnt(20)
	v_mfma_f32_16x16x32_bf16 v[128:131], v[112:115], v[132:135], v[128:131]
	v_add_u32_e32 v133, s61, v140
	s_cselect_b32 s21, s63, s57
	v_addc_co_u32_e32 v132, vcc, v140, v144, vcc
	v_subbrev_co_u32_e64 v133, s[4:5], 0, v133, s[4:5]
	s_add_i32 s23, s23, s21
	v_max_i32_e32 v132, 0, v132
	v_min_i32_e32 v133, s43, v133
	v_subrev_u32_e32 v132, s23, v132
	v_subrev_u32_e32 v133, s23, v133
	v_cmp_lt_i32_e32 vcc, 0, v132
	v_cmp_gt_i32_e64 s[4:5], 0, v133
	s_or_b64 vcc, vcc, s[4:5]
	v_cndmask_b32_e32 v134, v136, v219, vcc
	v_cmp_lt_i32_e32 vcc, 1, v132
	v_cmp_gt_i32_e64 s[4:5], 1, v133
	s_or_b64 vcc, vcc, s[4:5]
	v_cndmask_b32_e32 v135, v137, v219, vcc
	v_cmp_lt_i32_e32 vcc, 2, v132
	v_cmp_gt_i32_e64 s[4:5], 2, v133
	s_or_b64 vcc, vcc, s[4:5]
	v_cndmask_b32_e32 v140, v138, v219, vcc
	v_cmp_lt_i32_e32 vcc, 3, v132
	v_cmp_gt_i32_e64 s[4:5], 3, v133
	s_or_b64 vcc, vcc, s[4:5]
	v_cndmask_b32_e32 v166, v139, v219, vcc
	v_cmp_lt_i32_e32 vcc, 4, v132
	v_cmp_gt_i32_e64 s[4:5], 4, v133
	s_or_b64 vcc, vcc, s[4:5]
	v_cndmask_b32_e32 v128, v128, v219, vcc
	v_cmp_lt_i32_e32 vcc, 5, v132
	v_cmp_gt_i32_e64 s[4:5], 5, v133
	s_or_b64 vcc, vcc, s[4:5]
	v_cndmask_b32_e32 v167, v129, v219, vcc
	v_cmp_lt_i32_e32 vcc, 6, v132
	v_cmp_gt_i32_e64 s[4:5], 6, v133
	s_or_b64 vcc, vcc, s[4:5]
	v_cndmask_b32_e32 v130, v130, v219, vcc
	v_cmp_lt_i32_e32 vcc, 7, v132
	v_cmp_gt_i32_e64 s[4:5], 7, v133
	s_or_b64 vcc, vcc, s[4:5]
	v_and_b32_e32 v133, 64, v199
	v_max3_f32 v136, v134, s41, v135
	v_cndmask_b32_e32 v132, v131, v219, vcc
	v_xor_b32_e32 v131, 16, v199
	v_add_u32_e32 v133, 64, v133
	v_max3_f32 v136, v136, v140, v166
	v_cmp_lt_i32_e32 vcc, v131, v133
	v_max3_f32 v129, v136, v128, v167
	v_max3_f32 v129, v129, v130, v132
	v_cndmask_b32_e32 v131, v199, v131, vcc
	v_lshlrev_b32_e32 v233, 2, v131
	v_mov_b32_e32 v131, v129
	v_mov_b32_e32 v245, v129
	s_nop 1
	v_permlane16_swap_b32_e32 v131, v245
	v_max_f32_e32 v131, v131, v245
	v_mov_b32_e32 v169, v225
	s_mov_b32 s4, s56
	s_mov_b32 s5, s46
	v_mov_b32_e32 v182, v225
	s_waitcnt lgkmcnt(0)
	v_max_f32_e32 v131, v131, v131
	v_max_f32_e32 v129, v129, v131
	v_xor_b32_e32 v131, 32, v199
	v_cmp_lt_i32_e32 vcc, v131, v133
	v_mov_b32_e32 v185, v226
	v_mov_b32_e32 v186, v225
	v_cndmask_b32_e32 v131, v199, v131, vcc
	v_lshlrev_b32_e32 v234, 2, v131
	v_mov_b32_e32 v131, v129
	v_mov_b32_e32 v245, v129
	s_nop 1
	v_permlane32_swap_b32_e32 v131, v245
	v_max_f32_e32 v131, v131, v245
	s_add_i32 s62, s60, 2
	s_mov_b64 s[24:25], -1
	s_waitcnt lgkmcnt(0)
	v_max3_f32 v183, v143, v129, v131
	v_sub_f32_e32 v129, v134, v183
	v_mov_b32_e32 v134, v226
	ds_read_b128 v[136:139], v228 offset:2048
	v_sub_f32_e32 v168, v143, v183
	v_sub_f32_e32 v133, v140, v183
	ds_read_b128 v[140:143], v228 offset:3072
	s_waitcnt lgkmcnt(1)
	v_mfma_f32_16x16x32_bf16 v[162:165], v[124:127], v[136:139], 0
	v_ashrrev_i32_e32 v134, 4, v134
	v_sub_f32_e32 v131, v135, v183
	v_sub_f32_e32 v135, v166, v183
	v_mfma_f32_16x16x32_bf16 v[136:139], v[116:119], v[136:139], 0
	v_add_u32_e32 v166, s20, v134
	v_lshlrev_b32_e32 v134, 2, v134
	v_and_or_b32 v134, s4, 3, v134
	v_cndmask_b32_e64 v134, v134, v166, s[0:1]
	s_waitcnt lgkmcnt(0)
	v_mfma_f32_16x16x32_bf16 v[162:165], v[120:123], v[140:143], v[162:165]
	s_add_i32 s22, s5, s21
	v_cmp_gt_i32_e32 vcc, s4, v134
	v_cmp_lt_i32_e64 s[4:5], s4, v134
	v_mfma_f32_16x16x32_bf16 v[136:139], v[112:115], v[140:143], v[136:139]
	v_add_u32_e32 v141, s61, v169
	v_addc_co_u32_e32 v140, vcc, v169, v144, vcc
	v_subbrev_co_u32_e64 v134, s[4:5], 0, v141, s[4:5]
	v_max_i32_e32 v140, 0, v140
	v_min_i32_e32 v134, s43, v134
	v_subrev_u32_e32 v140, s22, v140
	v_subrev_u32_e32 v134, s22, v134
	v_cmp_lt_i32_e32 vcc, 0, v140
	v_cmp_gt_i32_e64 s[4:5], 0, v134
	s_or_b64 vcc, vcc, s[4:5]
	v_cndmask_b32_e32 v143, v162, v219, vcc
	v_cmp_lt_i32_e32 vcc, 1, v140
	v_cmp_gt_i32_e64 s[4:5], 1, v134
	s_or_b64 vcc, vcc, s[4:5]
	v_cndmask_b32_e32 v162, v163, v219, vcc
	v_cmp_lt_i32_e32 vcc, 2, v140
	v_cmp_gt_i32_e64 s[4:5], 2, v134
	s_or_b64 vcc, vcc, s[4:5]
	v_cndmask_b32_e32 v164, v164, v219, vcc
	v_cmp_lt_i32_e32 vcc, 3, v140
	v_cmp_gt_i32_e64 s[4:5], 3, v134
	s_or_b64 vcc, vcc, s[4:5]
	v_cndmask_b32_e32 v166, v165, v219, vcc
	v_cmp_lt_i32_e32 vcc, 4, v140
	v_cmp_gt_i32_e64 s[4:5], 4, v134
	s_or_b64 vcc, vcc, s[4:5]
	v_cndmask_b32_e32 v136, v136, v219, vcc
	v_cmp_lt_i32_e32 vcc, 5, v140
	v_cmp_gt_i32_e64 s[4:5], 5, v134
	s_or_b64 vcc, vcc, s[4:5]
	v_cndmask_b32_e32 v169, v137, v219, vcc
	v_cmp_lt_i32_e32 vcc, 6, v140
	v_cmp_gt_i32_e64 s[4:5], 6, v134
	s_or_b64 vcc, vcc, s[4:5]
	v_max3_f32 v141, v143, s41, v162
	v_cndmask_b32_e32 v170, v138, v219, vcc
	v_cmp_lt_i32_e32 vcc, 7, v140
	v_cmp_gt_i32_e64 s[4:5], 7, v134
	v_max3_f32 v141, v141, v164, v166
	s_or_b64 vcc, vcc, s[4:5]
	v_max3_f32 v137, v141, v136, v169
	v_cndmask_b32_e32 v171, v139, v219, vcc
	v_max3_f32 v134, v137, v170, v171
	v_mov_b32_e32 v138, v134
	v_mov_b32_e32 v245, v134
	s_nop 1
	v_permlane16_swap_b32_e32 v138, v245
	v_max_f32_e32 v138, v138, v245
	v_sub_f32_e32 v128, v128, v183
	v_exp_f32_e32 v137, v128
	v_sub_f32_e32 v128, v167, v183
	v_exp_f32_e32 v139, v128
	v_sub_f32_e32 v128, v130, v183
	s_waitcnt lgkmcnt(0)
; __device__ __forceinline__ void attn_step(int ks, const KVB& b, int L16, int r, int i0, int iq, int lane,
;                                           const bf16x8* qs, f32x4 (&o)[4], float& mrun, float& lrun) {
;     ...
;   f32x4 sa = __builtin_amdgcn_mfma_f32_16x16x32_bf16(b.k0, qB0, z, 0, 0, 0);
;   sa = __builtin_amdgcn_mfma_f32_16x16x32_bf16(b.k1, qB1, sa, 0, 0, 0);
;   f32x4 sb = __builtin_amdgcn_mfma_f32_16x16x32_bf16(b.k2, qB0, z, 0, 0, 0);
;   sb = __builtin_amdgcn_mfma_f32_16x16x32_bf16(b.k3, qB1, sb, 0, 0, 0);
;   int jlo = max(iq - D + (cV < r ? 1 : 0), 0) - sV;
;   int jhi = min(iq + D - (cV > r ? 1 : 0), L16 - 1) - sV;
;   const float NINF = -__builtin_inff();
;   float s8[8];
;   float mt = -1e30f;
; #pragma unroll
;   for (int j = 0; j < 8; ++j) {
;     float sv = j < 4 ? sa[j] : sb[j - 4];
;     sv = (j >= jlo && j <= jhi) ? sv : NINF;
;     s8[j] = sv;
;     mt = fmaxf(mt, sv);
;   }
;   mt = fmaxf(mt, __shfl_xor(mt, 16));
;   mt = fmaxf(mt, __shfl_xor(mt, 32));
;   float mnew = fmaxf(mrun, mt);
;   float alpha = __builtin_amdgcn_exp2f(mrun - mnew);
;   mrun = mnew;
;   float ps = 0.f;
;   float p8[8];
; #pragma unroll
;   for (int j = 0; j < 8; ++j) { p8[j] = __builtin_amdgcn_exp2f(s8[j] - mnew); ps += p8[j]; }
;   lrun = lrun * alpha + ps;
;   union { uint4 u; bf16x8 v; } pb;
;   pb.u = make_uint4(pack2(p8[0], p8[1]), pack2(p8[2], p8[3]), pack2(p8[4], p8[5]), pack2(p8[6], p8[7]));
; #pragma unroll
;   for (int dt = 0; dt < 4; ++dt) { o[dt][0] *= alpha; o[dt][1] *= alpha; o[dt][2] *= alpha; o[dt][3] *= alpha; }
;   o[0] = __builtin_amdgcn_mfma_f32_16x16x32_bf16(b.v0, pb.v, o[0], 0, 0, 0);
;   o[1] = __builtin_amdgcn_mfma_f32_16x16x32_bf16(b.v1, pb.v, o[1], 0, 0, 0);
;   o[2] = __builtin_amdgcn_mfma_f32_16x16x32_bf16(b.v2, pb.v, o[2], 0, 0, 0);
;   o[3] = __builtin_amdgcn_mfma_f32_16x16x32_bf16(b.v3, pb.v, o[3], 0, 0, 0);
	v_max_f32_e32 v130, v138, v138
	v_max_f32_e32 v130, v134, v130
	v_mov_b32_e32 v134, v130
	v_mov_b32_e32 v245, v130
	s_nop 1
	v_permlane32_swap_b32_e32 v134, v245
	v_max_f32_e32 v134, v134, v245
	v_exp_f32_e32 v142, v168
	v_exp_f32_e32 v141, v128
	v_sub_f32_e32 v128, v132, v183
	v_exp_f32_e32 v163, v128
	s_waitcnt lgkmcnt(0)
	v_max3_f32 v165, v237, v130, v134
	v_sub_f32_e32 v128, v143, v165
	v_pk_mul_f32 v[62:63], v[62:63], v[142:143] op_sel_hi:[1,0]
	v_pk_mul_f32 v[60:61], v[60:61], v[142:143] op_sel_hi:[1,0]
	v_sub_f32_e32 v143, v171, v165
	v_sub_f32_e32 v172, v237, v165
	v_sub_f32_e32 v130, v162, v165
	v_pk_mul_f32 v[58:59], v[58:59], v[142:143] op_sel_hi:[1,0]
	v_pk_mul_f32 v[56:57], v[56:57], v[142:143] op_sel_hi:[1,0]
	v_exp_f32_e32 v162, v143
	v_pk_mul_f32 v[54:55], v[54:55], v[142:143] op_sel_hi:[1,0]
	v_pk_mul_f32 v[52:53], v[52:53], v[142:143] op_sel_hi:[1,0]
	v_pk_mul_f32 v[46:47], v[46:47], v[142:143] op_sel_hi:[1,0]
	v_pk_mul_f32 v[44:45], v[44:45], v[142:143] op_sel_hi:[1,0]
	v_mov_b32_e32 v143, v226
	s_mov_b32 s4, s8
	s_mov_b32 s5, s46
	v_sub_f32_e32 v132, v164, v165
	v_sub_f32_e32 v140, v170, v165
	v_exp_f32_e32 v164, v172
	ds_read_b128 v[170:173], v228 offset:4096
	ds_read_b128 v[174:177], v228 offset:5120
	s_waitcnt lgkmcnt(1)
	v_mfma_f32_16x16x32_bf16 v[178:181], v[124:127], v[170:173], 0
	v_ashrrev_i32_e32 v143, 4, v143
	v_add_u32_e32 v184, s20, v143
	v_lshlrev_b32_e32 v143, 2, v143
	v_mfma_f32_16x16x32_bf16 v[170:173], v[116:119], v[170:173], 0
	v_and_or_b32 v143, s4, 3, v143
	v_cndmask_b32_e64 v143, v143, v184, s[0:1]
	s_add_i32 s22, s5, s21
	s_waitcnt lgkmcnt(0)
	v_mfma_f32_16x16x32_bf16 v[178:181], v[120:123], v[174:177], v[178:181]
	v_cmp_gt_i32_e32 vcc, s4, v143
	v_cmp_lt_i32_e64 s[4:5], s4, v143
	v_exp_f32_e32 v129, v129
	v_mfma_f32_16x16x32_bf16 v[170:173], v[112:115], v[174:177], v[170:173]
	v_add_u32_e32 v175, s61, v182
	v_addc_co_u32_e32 v174, vcc, v182, v144, vcc
	v_subbrev_co_u32_e64 v143, s[4:5], 0, v175, s[4:5]
	v_max_i32_e32 v174, 0, v174
	v_min_i32_e32 v143, s43, v143
	v_subrev_u32_e32 v174, s22, v174
	v_subrev_u32_e32 v143, s22, v143
	v_cmp_lt_i32_e32 vcc, 0, v174
	v_cmp_gt_i32_e64 s[4:5], 0, v143
	s_or_b64 vcc, vcc, s[4:5]
	v_cndmask_b32_e32 v175, v178, v219, vcc
	v_cmp_lt_i32_e32 vcc, 1, v174
	v_cmp_gt_i32_e64 s[4:5], 1, v143
	s_or_b64 vcc, vcc, s[4:5]
	v_cndmask_b32_e32 v176, v179, v219, vcc
	v_cmp_lt_i32_e32 vcc, 2, v174
	v_cmp_gt_i32_e64 s[4:5], 2, v143
	s_or_b64 vcc, vcc, s[4:5]
	v_cndmask_b32_e32 v178, v180, v219, vcc
	v_cmp_lt_i32_e32 vcc, 3, v174
	v_cmp_gt_i32_e64 s[4:5], 3, v143
	s_or_b64 vcc, vcc, s[4:5]
	v_cndmask_b32_e32 v182, v181, v219, vcc
	v_cmp_lt_i32_e32 vcc, 4, v174
	v_cmp_gt_i32_e64 s[4:5], 4, v143
	s_or_b64 vcc, vcc, s[4:5]
	v_cndmask_b32_e32 v170, v170, v219, vcc
	v_cmp_lt_i32_e32 vcc, 5, v174
	v_cmp_gt_i32_e64 s[4:5], 5, v143
	s_or_b64 vcc, vcc, s[4:5]
	v_cndmask_b32_e32 v184, v171, v219, vcc
	v_cmp_lt_i32_e32 vcc, 6, v174
	v_cmp_gt_i32_e64 s[4:5], 6, v143
	s_or_b64 vcc, vcc, s[4:5]
	v_max3_f32 v177, v175, s41, v176
	v_cndmask_b32_e32 v172, v172, v219, vcc
	v_cmp_lt_i32_e32 vcc, 7, v174
	v_cmp_gt_i32_e64 s[4:5], 7, v143
	v_max3_f32 v177, v177, v178, v182
	s_or_b64 vcc, vcc, s[4:5]
	v_max3_f32 v171, v177, v170, v184
	v_cndmask_b32_e32 v143, v173, v219, vcc
	v_max3_f32 v171, v171, v172, v143
	v_mov_b32_e32 v173, v171
	v_mov_b32_e32 v245, v171
	s_nop 1
	v_permlane16_swap_b32_e32 v173, v245
	v_max_f32_e32 v173, v173, v245
	v_exp_f32_e32 v131, v131
	v_exp_f32_e32 v133, v133
	v_exp_f32_e32 v135, v135
	v_sub_f32_e32 v134, v166, v165
	s_waitcnt lgkmcnt(0)
	v_max_f32_e32 v173, v173, v173
	v_max_f32_e32 v171, v171, v173
	v_sub_f32_e32 v136, v136, v165
	v_sub_f32_e32 v138, v169, v165
	v_mov_b32_e32 v173, v171
	v_mov_b32_e32 v245, v171
	s_nop 1
	v_permlane32_swap_b32_e32 v173, v245
	v_max_f32_e32 v173, v173, v245
	v_exp_f32_e32 v128, v128
	v_exp_f32_e32 v130, v130
	v_exp_f32_e32 v132, v132
	v_exp_f32_e32 v134, v134
	v_exp_f32_e32 v136, v136
	v_exp_f32_e32 v138, v138
	v_exp_f32_e32 v140, v140
	v_cvt_pk_bf16_f32 v166, v129, v131
	v_cvt_pk_bf16_f32 v167, v133, v135
	v_cvt_pk_bf16_f32 v168, v137, v139
	v_cvt_pk_bf16_f32 v169, v141, v163
	v_pk_mul_f32 v[50:51], v[50:51], v[164:165] op_sel_hi:[1,0]
	v_pk_mul_f32 v[48:49], v[48:49], v[164:165] op_sel_hi:[1,0]
	s_waitcnt vmcnt(15)
	v_mfma_f32_16x16x32_bf16 v[60:63], v[64:67], v[166:169], v[60:63]
	v_mul_f32_e64 v42, v42, v164
	v_mul_f32_e64 v43, v43, v164
	v_pk_mul_f32 v[40:41], v[40:41], v[164:165] op_sel_hi:[1,0]
	v_pk_mul_f32 v[38:39], v[38:39], v[164:165] op_sel_hi:[1,0]
	s_waitcnt vmcnt(14)
	v_mfma_f32_16x16x32_bf16 v[56:59], v[68:71], v[166:169], v[56:59]
	v_mul_f32_e64 v36, v36, v164
	v_mul_f32_e64 v37, v37, v164
	v_pk_mul_f32 v[30:31], v[30:31], v[164:165] op_sel_hi:[1,0]
	v_pk_mul_f32 v[28:29], v[28:29], v[164:165] op_sel_hi:[1,0]
	s_waitcnt vmcnt(13)
	v_mfma_f32_16x16x32_bf16 v[52:55], v[72:75], v[166:169], v[52:55]
	s_waitcnt lgkmcnt(0)
	v_max3_f32 v204, v236, v171, v173
	s_mov_b32 s4, s10
	s_mov_b32 s5, s46
	s_waitcnt vmcnt(12)
	v_mfma_f32_16x16x32_bf16 v[44:47], v[76:79], v[166:169], v[44:47]
	v_cvt_pk_bf16_f32 v166, v128, v130
	v_cvt_pk_bf16_f32 v167, v132, v134
	v_cvt_pk_bf16_f32 v168, v136, v138
	v_cvt_pk_bf16_f32 v169, v140, v162
	s_nop 1
	v_mfma_f32_16x16x32_bf16 v[48:51], v[64:67], v[166:169], v[48:51]
	v_mfma_f32_16x16x32_bf16 v[40:43], v[68:71], v[166:169], v[40:43]
	v_mfma_f32_16x16x32_bf16 v[36:39], v[72:75], v[166:169], v[36:39]
	v_mfma_f32_16x16x32_bf16 v[28:31], v[76:79], v[166:169], v[28:31]
	v_sub_f32_e32 v167, v175, v204
	v_sub_f32_e32 v168, v176, v204
	ds_read_b128 v[174:177], v228 offset:6144
	v_exp_f32_e32 v169, v168
	v_sub_f32_e32 v168, v178, v204
	ds_read_b128 v[178:181], v228 offset:7168
	s_waitcnt lgkmcnt(1)
; __device__ __forceinline__ void attn_step(int ks, const KVB& b, int L16, int r, int i0, int iq, int lane,
;                                           const bf16x8* qs, f32x4 (&o)[4], float& mrun, float& lrun) {
;     ...
;   f32x4 sa = __builtin_amdgcn_mfma_f32_16x16x32_bf16(b.k0, qB0, z, 0, 0, 0);
;   sa = __builtin_amdgcn_mfma_f32_16x16x32_bf16(b.k1, qB1, sa, 0, 0, 0);
;   f32x4 sb = __builtin_amdgcn_mfma_f32_16x16x32_bf16(b.k2, qB0, z, 0, 0, 0);
;   sb = __builtin_amdgcn_mfma_f32_16x16x32_bf16(b.k3, qB1, sb, 0, 0, 0);
;   int jlo = max(iq - D + (cV < r ? 1 : 0), 0) - sV;
;   int jhi = min(iq + D - (cV > r ? 1 : 0), L16 - 1) - sV;
;   const float NINF = -__builtin_inff();
;   float s8[8];
;   float mt = -1e30f;
; #pragma unroll
;   for (int j = 0; j < 8; ++j) {
;     float sv = j < 4 ? sa[j] : sb[j - 4];
;     sv = (j >= jlo && j <= jhi) ? sv : NINF;
;     s8[j] = sv;
;     mt = fmaxf(mt, sv);
;   }
;   mt = fmaxf(mt, __shfl_xor(mt, 16));
;   mt = fmaxf(mt, __shfl_xor(mt, 32));
;   float mnew = fmaxf(mrun, mt);
;   float alpha = __builtin_amdgcn_exp2f(mrun - mnew);
;   mrun = mnew;
;   float ps = 0.f;
;   float p8[8];
; #pragma unroll
;   for (int j = 0; j < 8; ++j) { p8[j] = __builtin_amdgcn_exp2f(s8[j] - mnew); ps += p8[j]; }
;   lrun = lrun * alpha + ps;
;   union { uint4 u; bf16x8 v; } pb;
;   pb.u = make_uint4(pack2(p8[0], p8[1]), pack2(p8[2], p8[3]), pack2(p8[4], p8[5]), pack2(p8[6], p8[7]));
; #pragma unroll
;   for (int dt = 0; dt < 4; ++dt) { o[dt][0] *= alpha; o[dt][1] *= alpha; o[dt][2] *= alpha; o[dt][3] *= alpha; }
;   o[0] = __builtin_amdgcn_mfma_f32_16x16x32_bf16(b.v0, pb.v, o[0], 0, 0, 0);
;   o[1] = __builtin_amdgcn_mfma_f32_16x16x32_bf16(b.v1, pb.v, o[1], 0, 0, 0);
;   o[2] = __builtin_amdgcn_mfma_f32_16x16x32_bf16(b.v2, pb.v, o[2], 0, 0, 0);
;   o[3] = __builtin_amdgcn_mfma_f32_16x16x32_bf16(b.v3, pb.v, o[3], 0, 0, 0);
; template <int NT>
; __device__ void attn_unitN(const P& p, int u) {
;     ...
;   for (int ks = 0; ks < 18; ks += 2) {
; #pragma unroll
;     for (int t = 0; t < NT; ++t)
;       attn_step(ks, bA, L16, rb + RS * t, i0, iq, lane, qs + t * 128, o[t], mrun[t], lrun[t]);
;     bA = attn_load_e<NT>(ks + 2, kbase, vbase, L16, rb, i0, lane);
; #pragma unroll
;     for (int t = 0; t < NT; ++t)
;       attn_step(ks + 1, bB, L16, rb + RS * t, i0, iq, lane, qs + t * 128, o[t], mrun[t], lrun[t]);
	v_mfma_f32_16x16x32_bf16 v[124:127], v[124:127], v[174:177], 0
	v_sub_f32_e32 v166, v236, v204
	v_exp_f32_e32 v171, v168
	v_sub_f32_e32 v168, v182, v204
	s_waitcnt lgkmcnt(0)
	v_mfma_f32_16x16x32_bf16 v[120:123], v[120:123], v[178:181], v[124:127]
	v_exp_f32_e32 v173, v168
	v_sub_f32_e32 v168, v170, v204
	v_exp_f32_e32 v167, v167
	v_ashrrev_i32_e32 v124, 4, v185
	v_mfma_f32_16x16x32_bf16 v[116:119], v[116:119], v[174:177], 0
	v_add_u32_e32 v125, s20, v124
	v_lshlrev_b32_e32 v124, 2, v124
	v_and_or_b32 v124, s4, 3, v124
	v_cndmask_b32_e64 v124, v124, v125, s[0:1]
	s_add_i32 s20, s5, s21
	v_mfma_f32_16x16x32_bf16 v[112:115], v[112:115], v[178:181], v[116:119]
	v_cmp_gt_i32_e32 vcc, s4, v124
	v_cmp_lt_i32_e64 s[4:5], s4, v124
	v_exp_f32_e32 v175, v168
	v_add_u32_e32 v117, s61, v186
	v_addc_co_u32_e32 v116, vcc, v186, v144, vcc
	v_subbrev_co_u32_e64 v117, s[4:5], 0, v117, s[4:5]
	v_max_i32_e32 v116, 0, v116
	v_min_i32_e32 v117, s43, v117
	v_subrev_u32_e32 v116, s20, v116
	v_subrev_u32_e32 v117, s20, v117
	v_cmp_lt_i32_e32 vcc, 0, v116
	v_cmp_gt_i32_e64 s[4:5], 0, v117
	s_or_b64 vcc, vcc, s[4:5]
	v_cndmask_b32_e32 v118, v120, v219, vcc
	v_cmp_lt_i32_e32 vcc, 1, v116
	v_cmp_gt_i32_e64 s[4:5], 1, v117
	s_or_b64 vcc, vcc, s[4:5]
	v_cndmask_b32_e32 v119, v121, v219, vcc
	v_cmp_lt_i32_e32 vcc, 2, v116
	v_cmp_gt_i32_e64 s[4:5], 2, v117
	s_or_b64 vcc, vcc, s[4:5]
	v_cndmask_b32_e32 v121, v122, v219, vcc
	v_cmp_lt_i32_e32 vcc, 3, v116
	v_cmp_gt_i32_e64 s[4:5], 3, v117
	s_or_b64 vcc, vcc, s[4:5]
	v_cndmask_b32_e32 v122, v123, v219, vcc
	v_cmp_lt_i32_e32 vcc, 4, v116
	v_cmp_gt_i32_e64 s[4:5], 4, v117
	s_or_b64 vcc, vcc, s[4:5]
	v_cndmask_b32_e32 v112, v112, v219, vcc
	v_cmp_lt_i32_e32 vcc, 5, v116
	v_cmp_gt_i32_e64 s[4:5], 5, v117
	s_or_b64 vcc, vcc, s[4:5]
	v_cndmask_b32_e32 v113, v113, v219, vcc
	v_cmp_lt_i32_e32 vcc, 6, v116
	v_cmp_gt_i32_e64 s[4:5], 6, v117
	s_or_b64 vcc, vcc, s[4:5]
	v_max3_f32 v120, v118, s41, v119
	v_cndmask_b32_e32 v114, v114, v219, vcc
	v_cmp_lt_i32_e32 vcc, 7, v116
	v_cmp_gt_i32_e64 s[4:5], 7, v117
	v_max3_f32 v120, v120, v121, v122
	s_or_b64 vcc, vcc, s[4:5]
	v_max3_f32 v120, v120, v112, v113
	v_cndmask_b32_e32 v116, v115, v219, vcc
	v_max3_f32 v115, v120, v114, v116
	v_mov_b32_e32 v117, v115
	v_mov_b32_e32 v245, v115
	s_nop 1
	v_permlane16_swap_b32_e32 v117, v245
	v_max_f32_e32 v117, v117, v245
	v_sub_f32_e32 v120, v184, v204
	v_exp_f32_e32 v177, v120
	v_sub_f32_e32 v120, v172, v204
	v_exp_f32_e32 v144, v166
	s_waitcnt lgkmcnt(0)
	v_max_f32_e32 v117, v117, v117
	v_max_f32_e32 v115, v115, v117
	v_mov_b32_e32 v117, v115
	v_mov_b32_e32 v245, v115
	s_nop 1
	v_permlane32_swap_b32_e32 v117, v245
	v_max_f32_e32 v117, v117, v245
	v_exp_f32_e32 v179, v120
	v_sub_f32_e32 v120, v143, v204
	s_add_i32 s4, s59, -4
	v_exp_f32_e32 v181, v120
	s_waitcnt lgkmcnt(0)
	v_max3_f32 v203, v235, v115, v117
	v_sub_f32_e32 v115, v118, v203
	v_exp_f32_e32 v166, v115
	v_sub_f32_e32 v115, v119, v203
	v_sub_f32_e32 v112, v112, v203
	v_exp_f32_e32 v168, v115
	v_sub_f32_e32 v115, v121, v203
	v_exp_f32_e32 v174, v112
	v_sub_f32_e32 v112, v113, v203
	v_sub_f32_e32 v117, v235, v203
	v_exp_f32_e32 v170, v115
	v_sub_f32_e32 v115, v122, v203
	v_exp_f32_e32 v176, v112
	v_sub_f32_e32 v112, v114, v203
	v_sub_f32_e32 v116, v116, v203
	s_and_b32 s65, s4, 8
	v_exp_f32_e32 v172, v115
	v_exp_f32_e32 v178, v112
	v_exp_f32_e32 v180, v116
	v_exp_f32_e32 v182, v117
	s_xor_b32 s22, s65, 8
	s_cmp_gt_u32 s60, 15
	s_cselect_b64 s[20:21], -1, 0
	v_pk_mul_f32 v[34:35], v[34:35], v[144:145] op_sel_hi:[1,0]
	v_pk_mul_f32 v[32:33], v[32:33], v[144:145] op_sel_hi:[1,0]
	v_cvt_pk_bf16_f32 v112, v167, v169
	v_cvt_pk_bf16_f32 v113, v171, v173
	v_cvt_pk_bf16_f32 v114, v175, v177
	v_cvt_pk_bf16_f32 v115, v179, v181
	v_pk_mul_f32 v[26:27], v[26:27], v[144:145] op_sel_hi:[1,0]
	v_pk_mul_f32 v[24:25], v[24:25], v[144:145] op_sel_hi:[1,0]
	v_pk_mul_f32 v[22:23], v[22:23], v[144:145] op_sel_hi:[1,0]
	v_pk_mul_f32 v[20:21], v[20:21], v[144:145] op_sel_hi:[1,0]
	v_pk_mul_f32 v[14:15], v[14:15], v[144:145] op_sel_hi:[1,0]
	v_pk_mul_f32 v[12:13], v[12:13], v[144:145] op_sel_hi:[1,0]
	s_and_b64 s[4:5], s[20:21], exec
	v_mfma_f32_16x16x32_bf16 v[32:35], v[64:67], v[112:115], v[32:35]
	v_mul_f32_e64 v18, v18, v182
	v_mul_f32_e64 v19, v19, v182
	v_pk_mul_f32 v[16:17], v[16:17], v[182:183] op_sel_hi:[1,0]
	v_pk_mul_f32 v[10:11], v[10:11], v[182:183] op_sel_hi:[1,0]
	v_mfma_f32_16x16x32_bf16 v[24:27], v[68:71], v[112:115], v[24:27]
	v_mul_f32_e64 v8, v8, v182
	v_mul_f32_e64 v9, v9, v182
	v_pk_mul_f32 v[6:7], v[6:7], v[182:183] op_sel_hi:[1,0]
	v_pk_mul_f32 v[4:5], v[4:5], v[182:183] op_sel_hi:[1,0]
	v_mfma_f32_16x16x32_bf16 v[20:23], v[72:75], v[112:115], v[20:23]
	v_mul_f32_e64 v2, v2, v182
	v_mul_f32_e64 v3, v3, v182
	v_pk_mul_f32 v[0:1], v[0:1], v[182:183] op_sel_hi:[1,0]
	s_cselect_b32 s66, s22, 0
	v_mfma_f32_16x16x32_bf16 v[12:15], v[76:79], v[112:115], v[12:15]
	v_cvt_pk_bf16_f32 v112, v166, v168
	v_cvt_pk_bf16_f32 v113, v170, v172
	v_cvt_pk_bf16_f32 v114, v174, v176
	v_cvt_pk_bf16_f32 v115, v178, v180
	s_add_i32 s66, s66, s42
	s_cmp_gt_u32 s60, 9
	v_mfma_f32_16x16x32_bf16 v[16:19], v[64:67], v[112:115], v[16:19]
	s_cselect_b64 s[22:23], -1, 0
	s_and_b64 vcc, exec, s[22:23]
	v_mfma_f32_16x16x32_bf16 v[8:11], v[68:71], v[112:115], v[8:11]
	v_mfma_f32_16x16x32_bf16 v[4:7], v[72:75], v[112:115], v[4:7]
	v_mfma_f32_16x16x32_bf16 v[0:3], v[76:79], v[112:115], v[0:3]
	s_cbranch_vccz .LBB0_238
	s_mov_b64 vcc, s[4:5]
	s_cbranch_vccz .LBB0_235
	v_lshl_add_u32 v64, s62, 5, v231
	s_mov_b64 s[24:25], 0

; __device__ __forceinline__ void attn_step(int ks, const KVB& b, int L16, int r, int i0, int iq, int lane,
;                                           const bf16x8* qs, f32x4 (&o)[4], float& mrun, float& lrun) {
;     ...
;   f32x4 sa = __builtin_amdgcn_mfma_f32_16x16x32_bf16(b.k0, qB0, z, 0, 0, 0);
;   sa = __builtin_amdgcn_mfma_f32_16x16x32_bf16(b.k1, qB1, sa, 0, 0, 0);
;   f32x4 sb = __builtin_amdgcn_mfma_f32_16x16x32_bf16(b.k2, qB0, z, 0, 0, 0);
;   sb = __builtin_amdgcn_mfma_f32_16x16x32_bf16(b.k3, qB1, sb, 0, 0, 0);
;   int jlo = max(iq - D + (cV < r ? 1 : 0), 0) - sV;
;   int jhi = min(iq + D - (cV > r ? 1 : 0), L16 - 1) - sV;
;   const float NINF = -__builtin_inff();
;   float s8[8];
;   float mt = -1e30f;
; #pragma unroll
;   for (int j = 0; j < 8; ++j) {
;     float sv = j < 4 ? sa[j] : sb[j - 4];
;     sv = (j >= jlo && j <= jhi) ? sv : NINF;
;     s8[j] = sv;
;     mt = fmaxf(mt, sv);
;   }
;   mt = fmaxf(mt, __shfl_xor(mt, 16));
;   mt = fmaxf(mt, __shfl_xor(mt, 32));
;   float mnew = fmaxf(mrun, mt);
;   float alpha = __builtin_amdgcn_exp2f(mrun - mnew);
;   mrun = mnew;
;   float ps = 0.f;
;   float p8[8];
; #pragma unroll
;   for (int j = 0; j < 8; ++j) { p8[j] = __builtin_amdgcn_exp2f(s8[j] - mnew); ps += p8[j]; }
; template <int NT>
; __device__ void attn_unitN(const P& p, int u) {
;     ...
;   for (int ks = 0; ks < 18; ks += 2) {
; #pragma unroll
;     for (int t = 0; t < NT; ++t)
;       attn_step(ks, bA, L16, rb + RS * t, i0, iq, lane, qs + t * 128, o[t], mrun[t], lrun[t]);
;     bA = attn_load_e<NT>(ks + 2, kbase, vbase, L16, rb, i0, lane);
; #pragma unroll
;     for (int t = 0; t < NT; ++t)
;       attn_step(ks + 1, bB, L16, rb + RS * t, i0, iq, lane, qs + t * 128, o[t], mrun[t], lrun[t]);
;     bB = attn_load_e<NT>(ks + 3, kbase, vbase, L16, rb, i0, lane);
;   }
.LBB0_248:
	v_ashrrev_i32_e32 v65, 31, v64
	v_ashrrev_i32_e32 v66, 2, v66
	v_lshlrev_b64 v[64:65], s44, v[64:65]
	v_ashrrev_i32_e32 v67, 31, v66
	v_lshl_add_u64 v[64:65], v[64:65], 0, v[66:67]
	v_lshlrev_b64 v[64:65], 9, v[64:65]
	v_lshl_add_u64 v[78:79], v[158:159], 0, v[64:65]
	v_mov_b32_e32 v143, v226
	v_mov_b32_e32 v196, v225
	s_mov_b32 s24, s42
	s_mov_b32 s25, s46
	global_load_dwordx2 v[64:65], v[78:79], off
	global_load_dwordx2 v[68:69], v[78:79], off offset:128
	global_load_dwordx2 v[72:73], v[78:79], off offset:256
	global_load_dwordx2 v[76:77], v[78:79], off offset:384
	global_load_dwordx2 v[66:67], v[78:79], off offset:512
	global_load_dwordx2 v[70:71], v[78:79], off offset:640
	global_load_dwordx2 v[74:75], v[78:79], off offset:768
	s_nop 0
	global_load_dwordx2 v[78:79], v[78:79], off offset:896
	ds_read_b128 v[184:187], v228
	ds_read_b128 v[188:191], v228 offset:1024
	s_add_i32 s4, s59, -8
	s_waitcnt vmcnt(23) lgkmcnt(1)
	v_mfma_f32_16x16x32_bf16 v[192:195], v[108:111], v[184:187], 0
	s_and_b32 s22, s4, 12
	v_ashrrev_i32_e32 v143, 4, v143
	v_add_u32_e32 v197, s22, v143
	s_waitcnt vmcnt(21)
	v_mfma_f32_16x16x32_bf16 v[184:187], v[100:103], v[184:187], 0
	v_lshlrev_b32_e32 v143, 2, v143
	s_add_i32 s23, s57, 8
	v_and_or_b32 v143, s24, 3, v143
	v_cndmask_b32_e64 v143, v143, v197, s[0:1]
	s_and_b64 s[4:5], s[0:1], exec
	s_waitcnt lgkmcnt(0)
	v_mfma_f32_16x16x32_bf16 v[192:195], v[104:107], v[188:191], v[192:195]
	v_mov_b32_e32 v218, s64
	v_cmp_gt_i32_e32 vcc, s24, v143
	v_cmp_lt_i32_e64 s[4:5], s24, v143
	s_waitcnt vmcnt(20)
	v_mfma_f32_16x16x32_bf16 v[184:187], v[96:99], v[188:191], v[184:187]
	v_add_u32_e32 v189, s61, v196
	s_cselect_b32 s23, s63, s23
	v_addc_co_u32_e32 v188, vcc, v196, v218, vcc
	v_subbrev_co_u32_e64 v143, s[4:5], 0, v189, s[4:5]
	s_add_i32 s25, s25, s23
	v_max_i32_e32 v188, 0, v188
	v_min_i32_e32 v143, s43, v143
	v_subrev_u32_e32 v188, s25, v188
	v_subrev_u32_e32 v143, s25, v143
	v_cmp_lt_i32_e32 vcc, 0, v188
	v_cmp_gt_i32_e64 s[4:5], 0, v143
	s_or_b64 vcc, vcc, s[4:5]
	v_cndmask_b32_e32 v189, v192, v219, vcc
	v_cmp_lt_i32_e32 vcc, 1, v188
	v_cmp_gt_i32_e64 s[4:5], 1, v143
	s_or_b64 vcc, vcc, s[4:5]
	v_cndmask_b32_e32 v190, v193, v219, vcc
	v_cmp_lt_i32_e32 vcc, 2, v188
	v_cmp_gt_i32_e64 s[4:5], 2, v143
	s_or_b64 vcc, vcc, s[4:5]
	v_cndmask_b32_e32 v196, v194, v219, vcc
	v_cmp_lt_i32_e32 vcc, 3, v188
	v_cmp_gt_i32_e64 s[4:5], 3, v143
	s_or_b64 vcc, vcc, s[4:5]
	v_cndmask_b32_e32 v197, v195, v219, vcc
	v_cmp_lt_i32_e32 vcc, 4, v188
	v_cmp_gt_i32_e64 s[4:5], 4, v143
	s_or_b64 vcc, vcc, s[4:5]
	v_cndmask_b32_e32 v184, v184, v219, vcc
	v_cmp_lt_i32_e32 vcc, 5, v188
	v_cmp_gt_i32_e64 s[4:5], 5, v143
	s_or_b64 vcc, vcc, s[4:5]
	v_cndmask_b32_e32 v198, v185, v219, vcc
	v_cmp_lt_i32_e32 vcc, 6, v188
	v_cmp_gt_i32_e64 s[4:5], 6, v143
	s_or_b64 vcc, vcc, s[4:5]
	v_max3_f32 v191, v189, s41, v190
	v_cndmask_b32_e32 v186, v186, v219, vcc
	v_cmp_lt_i32_e32 vcc, 7, v188
	v_cmp_gt_i32_e64 s[4:5], 7, v143
	v_max3_f32 v191, v191, v196, v197
	s_or_b64 vcc, vcc, s[4:5]
	v_max3_f32 v185, v191, v184, v198
	v_cndmask_b32_e32 v188, v187, v219, vcc
	v_max3_f32 v143, v185, v186, v188
	v_mov_b32_e32 v185, v143
	v_mov_b32_e32 v245, v143
	s_nop 1
	v_permlane16_swap_b32_e32 v185, v245
	v_max_f32_e32 v185, v185, v245
	v_mov_b32_e32 v200, v225
	s_mov_b32 s4, s56
	s_mov_b32 s5, s46
	s_waitcnt lgkmcnt(0)
	v_max_f32_e32 v185, v185, v185
	v_max_f32_e32 v143, v143, v185
	v_mov_b32_e32 v185, v143
	v_mov_b32_e32 v245, v143
	s_nop 1
	v_permlane32_swap_b32_e32 v185, v245
	v_max_f32_e32 v185, v185, v245
	s_waitcnt lgkmcnt(0)
	v_max3_f32 v143, v183, v143, v185
	v_sub_f32_e32 v187, v190, v143
	v_mov_b32_e32 v190, v226
	ds_read_b128 v[192:195], v228 offset:2048
	ds_read_b128 v[206:209], v228 offset:3072
	v_ashrrev_i32_e32 v190, 4, v190
	v_sub_f32_e32 v185, v189, v143
	v_sub_f32_e32 v189, v196, v143
	v_add_u32_e32 v196, s22, v190
	v_lshlrev_b32_e32 v190, 2, v190
	s_waitcnt lgkmcnt(1)
	v_mfma_f32_16x16x32_bf16 v[210:213], v[108:111], v[192:195], 0
	v_and_or_b32 v190, s4, 3, v190
	v_cndmask_b32_e64 v190, v190, v196, s[0:1]
	v_sub_f32_e32 v191, v197, v143
	s_add_i32 s24, s5, s23
	v_cmp_gt_i32_e32 vcc, s4, v190
	v_add_u32_e32 v197, s61, v200
	v_cmp_lt_i32_e64 s[4:5], s4, v190
	v_addc_co_u32_e32 v196, vcc, v200, v218, vcc
	s_nop 0
	v_subbrev_co_u32_e64 v190, s[4:5], 0, v197, s[4:5]
	s_waitcnt lgkmcnt(0)
	v_mfma_f32_16x16x32_bf16 v[210:213], v[104:107], v[206:209], v[210:213]
	v_max_i32_e32 v196, 0, v196
	v_min_i32_e32 v190, s43, v190
	v_subrev_u32_e32 v196, s24, v196
	v_subrev_u32_e32 v190, s24, v190
	v_cmp_lt_i32_e32 vcc, 0, v196
	v_cmp_gt_i32_e64 s[4:5], 0, v190
	s_or_b64 vcc, vcc, s[4:5]
	v_mfma_f32_16x16x32_bf16 v[192:195], v[100:103], v[192:195], 0
	v_cndmask_b32_e32 v200, v210, v219, vcc
	v_cmp_lt_i32_e32 vcc, 1, v196
	v_cmp_gt_i32_e64 s[4:5], 1, v190
	s_or_b64 vcc, vcc, s[4:5]
	v_cndmask_b32_e32 v202, v211, v219, vcc
	v_cmp_lt_i32_e32 vcc, 2, v196
	v_cmp_gt_i32_e64 s[4:5], 2, v190
	s_or_b64 vcc, vcc, s[4:5]
	v_mfma_f32_16x16x32_bf16 v[192:195], v[96:99], v[206:209], v[192:195]
	v_cndmask_b32_e32 v205, v212, v219, vcc
	v_cmp_lt_i32_e32 vcc, 3, v196
	v_cmp_gt_i32_e64 s[4:5], 3, v190
	s_or_b64 vcc, vcc, s[4:5]
	v_cndmask_b32_e32 v206, v213, v219, vcc
	v_cmp_lt_i32_e32 vcc, 4, v196
	v_cmp_gt_i32_e64 s[4:5], 4, v190
	s_or_b64 vcc, vcc, s[4:5]
	v_cndmask_b32_e32 v192, v192, v219, vcc
	v_cmp_lt_i32_e32 vcc, 5, v196
	v_cmp_gt_i32_e64 s[4:5], 5, v190
	s_or_b64 vcc, vcc, s[4:5]
	v_cndmask_b32_e32 v207, v193, v219, vcc
	v_cmp_lt_i32_e32 vcc, 6, v196
	v_cmp_gt_i32_e64 s[4:5], 6, v190
	s_or_b64 vcc, vcc, s[4:5]
	v_max3_f32 v197, v200, s41, v202
	v_cndmask_b32_e32 v208, v194, v219, vcc
	v_cmp_lt_i32_e32 vcc, 7, v196
	v_cmp_gt_i32_e64 s[4:5], 7, v190
	v_max3_f32 v197, v197, v205, v206
	s_or_b64 vcc, vcc, s[4:5]
	v_max3_f32 v193, v197, v192, v207
	v_cndmask_b32_e32 v210, v195, v219, vcc
	v_max3_f32 v190, v193, v208, v210
	v_mov_b32_e32 v194, v190
	v_mov_b32_e32 v245, v190
	s_nop 1
	v_permlane16_swap_b32_e32 v194, v245
	v_max_f32_e32 v194, v194, v245
	v_sub_f32_e32 v184, v184, v143
	v_exp_f32_e32 v193, v184
	v_sub_f32_e32 v184, v198, v143
	v_exp_f32_e32 v195, v184
	v_sub_f32_e32 v184, v186, v143
	s_waitcnt lgkmcnt(0)
; __device__ __forceinline__ void attn_step(int ks, const KVB& b, int L16, int r, int i0, int iq, int lane,
;                                           const bf16x8* qs, f32x4 (&o)[4], float& mrun, float& lrun) {
;     ...
;   f32x4 sa = __builtin_amdgcn_mfma_f32_16x16x32_bf16(b.k0, qB0, z, 0, 0, 0);
;   sa = __builtin_amdgcn_mfma_f32_16x16x32_bf16(b.k1, qB1, sa, 0, 0, 0);
;   f32x4 sb = __builtin_amdgcn_mfma_f32_16x16x32_bf16(b.k2, qB0, z, 0, 0, 0);
;   sb = __builtin_amdgcn_mfma_f32_16x16x32_bf16(b.k3, qB1, sb, 0, 0, 0);
;   int jlo = max(iq - D + (cV < r ? 1 : 0), 0) - sV;
;   int jhi = min(iq + D - (cV > r ? 1 : 0), L16 - 1) - sV;
;   const float NINF = -__builtin_inff();
;   float s8[8];
;   float mt = -1e30f;
; #pragma unroll
;   for (int j = 0; j < 8; ++j) {
;     float sv = j < 4 ? sa[j] : sb[j - 4];
;     sv = (j >= jlo && j <= jhi) ? sv : NINF;
;     s8[j] = sv;
;     mt = fmaxf(mt, sv);
;   }
;   mt = fmaxf(mt, __shfl_xor(mt, 16));
;   mt = fmaxf(mt, __shfl_xor(mt, 32));
;   float mnew = fmaxf(mrun, mt);
;   float alpha = __builtin_amdgcn_exp2f(mrun - mnew);
;   mrun = mnew;
;   float ps = 0.f;
;   float p8[8];
; #pragma unroll
;   for (int j = 0; j < 8; ++j) { p8[j] = __builtin_amdgcn_exp2f(s8[j] - mnew); ps += p8[j]; }
;   lrun = lrun * alpha + ps;
;   union { uint4 u; bf16x8 v; } pb;
;   pb.u = make_uint4(pack2(p8[0], p8[1]), pack2(p8[2], p8[3]), pack2(p8[4], p8[5]), pack2(p8[6], p8[7]));
; #pragma unroll
;   for (int dt = 0; dt < 4; ++dt) { o[dt][0] *= alpha; o[dt][1] *= alpha; o[dt][2] *= alpha; o[dt][3] *= alpha; }
;   o[0] = __builtin_amdgcn_mfma_f32_16x16x32_bf16(b.v0, pb.v, o[0], 0, 0, 0);
;   o[1] = __builtin_amdgcn_mfma_f32_16x16x32_bf16(b.v1, pb.v, o[1], 0, 0, 0);
;   o[2] = __builtin_amdgcn_mfma_f32_16x16x32_bf16(b.v2, pb.v, o[2], 0, 0, 0);
;   o[3] = __builtin_amdgcn_mfma_f32_16x16x32_bf16(b.v3, pb.v, o[3], 0, 0, 0);
	v_max_f32_e32 v186, v194, v194
	v_max_f32_e32 v186, v190, v186
	v_mov_b32_e32 v190, v186
	v_mov_b32_e32 v245, v186
	s_nop 1
	v_permlane32_swap_b32_e32 v190, v245
	v_max_f32_e32 v190, v190, v245
	v_sub_f32_e32 v183, v183, v143
	v_exp_f32_e32 v197, v184
	v_sub_f32_e32 v184, v188, v143
	v_exp_f32_e32 v198, v183
	s_waitcnt lgkmcnt(0)
	v_max3_f32 v237, v165, v186, v190
	v_sub_f32_e32 v183, v200, v237
	v_exp_f32_e32 v201, v184
	v_exp_f32_e32 v184, v183
	v_sub_f32_e32 v183, v202, v237
	v_exp_f32_e32 v186, v183
	v_sub_f32_e32 v183, v205, v237
	v_exp_f32_e32 v188, v183
	v_sub_f32_e32 v183, v206, v237
	v_exp_f32_e32 v190, v183
	v_sub_f32_e32 v183, v192, v237
	v_exp_f32_e32 v192, v183
	v_sub_f32_e32 v183, v207, v237
	v_exp_f32_e32 v194, v183
	v_sub_f32_e32 v183, v208, v237
	v_sub_f32_e32 v165, v165, v237
	v_exp_f32_e32 v196, v183
	v_sub_f32_e32 v183, v210, v237
	v_exp_f32_e32 v200, v183
	v_exp_f32_e32 v202, v165
	v_mov_b32_e32 v165, v226
	v_mov_b32_e32 v183, v225
	s_mov_b32 s4, s8
	s_mov_b32 s5, s46
	ds_read_b128 v[210:213], v228 offset:4096
	ds_read_b128 v[214:217], v228 offset:5120
	v_ashrrev_i32_e32 v165, 4, v165
	v_add_u32_e32 v205, s22, v165
	v_lshlrev_b32_e32 v165, 2, v165
	v_and_or_b32 v165, s4, 3, v165
	s_waitcnt lgkmcnt(1)
	v_mfma_f32_16x16x32_bf16 v[220:223], v[108:111], v[210:213], 0
	v_cndmask_b32_e64 v165, v165, v205, s[0:1]
	v_cmp_gt_i32_e32 vcc, s4, v165
	s_add_i32 s24, s5, s23
	v_cmp_lt_i32_e64 s[4:5], s4, v165
	v_addc_co_u32_e32 v205, vcc, v183, v218, vcc
	v_add_u32_e32 v183, s61, v183
	v_subbrev_co_u32_e64 v165, s[4:5], 0, v183, s[4:5]
	s_waitcnt lgkmcnt(0)
	v_mfma_f32_16x16x32_bf16 v[220:223], v[104:107], v[214:217], v[220:223]
	v_max_i32_e32 v205, 0, v205
	v_min_i32_e32 v165, s43, v165
	v_subrev_u32_e32 v205, s24, v205
	v_subrev_u32_e32 v165, s24, v165
	v_mfma_f32_16x16x32_bf16 v[210:213], v[100:103], v[210:213], 0
	v_cmp_lt_i32_e32 vcc, 0, v205
	v_cmp_gt_i32_e64 s[4:5], 0, v165
	s_or_b64 vcc, vcc, s[4:5]
	v_cndmask_b32_e32 v183, v220, v219, vcc
	v_cmp_lt_i32_e32 vcc, 1, v205
	v_cmp_gt_i32_e64 s[4:5], 1, v165
	s_or_b64 vcc, vcc, s[4:5]
	v_mfma_f32_16x16x32_bf16 v[210:213], v[96:99], v[214:217], v[210:213]
	v_cndmask_b32_e32 v214, v221, v219, vcc
	v_cmp_lt_i32_e32 vcc, 2, v205
	v_cmp_gt_i32_e64 s[4:5], 2, v165
	s_or_b64 vcc, vcc, s[4:5]
	v_cndmask_b32_e32 v216, v222, v219, vcc
	v_cmp_lt_i32_e32 vcc, 3, v205
	v_cmp_gt_i32_e64 s[4:5], 3, v165
	s_or_b64 vcc, vcc, s[4:5]
	v_cndmask_b32_e32 v217, v223, v219, vcc
	v_cmp_lt_i32_e32 vcc, 4, v205
	v_cmp_gt_i32_e64 s[4:5], 4, v165
	s_or_b64 vcc, vcc, s[4:5]
	v_cndmask_b32_e32 v210, v210, v219, vcc
	v_cmp_lt_i32_e32 vcc, 5, v205
	v_cmp_gt_i32_e64 s[4:5], 5, v165
	s_or_b64 vcc, vcc, s[4:5]
	v_cndmask_b32_e32 v235, v211, v219, vcc
	v_cmp_lt_i32_e32 vcc, 6, v205
	v_cmp_gt_i32_e64 s[4:5], 6, v165
	s_or_b64 vcc, vcc, s[4:5]
	v_max3_f32 v215, v183, s41, v214
	v_cndmask_b32_e32 v242, v212, v219, vcc
	v_cmp_lt_i32_e32 vcc, 7, v205
	v_cmp_gt_i32_e64 s[4:5], 7, v165
	v_max3_f32 v215, v215, v216, v217
	s_or_b64 vcc, vcc, s[4:5]
	v_max3_f32 v211, v215, v210, v235
	v_cndmask_b32_e32 v165, v213, v219, vcc
	v_max3_f32 v205, v211, v242, v165
	v_mov_b32_e32 v211, v205
	v_mov_b32_e32 v245, v205
	s_nop 1
	v_permlane16_swap_b32_e32 v211, v245
	v_max_f32_e32 v211, v211, v245
	v_exp_f32_e32 v185, v185
	v_exp_f32_e32 v187, v187
	v_exp_f32_e32 v189, v189
	v_exp_f32_e32 v191, v191
	s_waitcnt lgkmcnt(0)
	v_max_f32_e32 v211, v211, v211
	v_max_f32_e32 v205, v205, v211
	v_mov_b32_e32 v211, v205
	v_mov_b32_e32 v245, v205
	s_nop 1
	v_permlane32_swap_b32_e32 v211, v245
	v_max_f32_e32 v211, v211, v245
	v_pk_mul_f32 v[62:63], v[62:63], v[198:199] op_sel_hi:[1,0]
	v_pk_mul_f32 v[60:61], v[60:61], v[198:199] op_sel_hi:[1,0]
	v_cvt_pk_bf16_f32 v206, v185, v187
	v_cvt_pk_bf16_f32 v207, v189, v191
	v_cvt_pk_bf16_f32 v208, v193, v195
	v_cvt_pk_bf16_f32 v209, v197, v201
	v_pk_mul_f32 v[58:59], v[58:59], v[198:199] op_sel_hi:[1,0]
	v_pk_mul_f32 v[56:57], v[56:57], v[198:199] op_sel_hi:[1,0]
	v_pk_mul_f32 v[54:55], v[54:55], v[198:199] op_sel_hi:[1,0]
	v_pk_mul_f32 v[52:53], v[52:53], v[198:199] op_sel_hi:[1,0]
	v_pk_mul_f32 v[46:47], v[46:47], v[198:199] op_sel_hi:[1,0]
	v_pk_mul_f32 v[44:45], v[44:45], v[198:199] op_sel_hi:[1,0]
	s_waitcnt vmcnt(15)
	v_mfma_f32_16x16x32_bf16 v[60:63], v[80:83], v[206:209], v[60:63]
	v_mul_f32_e64 v50, v50, v202
	v_mul_f32_e64 v51, v51, v202
	v_pk_mul_f32 v[48:49], v[48:49], v[202:203] op_sel_hi:[1,0]
	v_pk_mul_f32 v[42:43], v[42:43], v[202:203] op_sel_hi:[1,0]
	s_waitcnt vmcnt(14)
	v_mfma_f32_16x16x32_bf16 v[56:59], v[84:87], v[206:209], v[56:59]
	v_mul_f32_e64 v40, v40, v202
	v_mul_f32_e64 v41, v41, v202
	v_pk_mul_f32 v[38:39], v[38:39], v[202:203] op_sel_hi:[1,0]
	v_pk_mul_f32 v[36:37], v[36:37], v[202:203] op_sel_hi:[1,0]
	s_waitcnt vmcnt(13)
	v_mfma_f32_16x16x32_bf16 v[52:55], v[88:91], v[206:209], v[52:55]
	v_mul_f32_e64 v30, v30, v202
	v_mul_f32_e64 v31, v31, v202
	v_pk_mul_f32 v[28:29], v[28:29], v[202:203] op_sel_hi:[1,0]
	s_waitcnt lgkmcnt(0)
	v_max3_f32 v236, v204, v205, v211
	s_waitcnt vmcnt(12)
	v_mfma_f32_16x16x32_bf16 v[44:47], v[92:95], v[206:209], v[44:47]
	v_cvt_pk_bf16_f32 v206, v184, v186
	v_cvt_pk_bf16_f32 v207, v188, v190
	v_cvt_pk_bf16_f32 v208, v192, v194
	v_cvt_pk_bf16_f32 v209, v196, v200
	v_sub_f32_e32 v183, v183, v236
	s_mov_b32 s4, s10
	v_mfma_f32_16x16x32_bf16 v[48:51], v[80:83], v[206:209], v[48:51]
	s_mov_b32 s5, s46
	v_exp_f32_e32 v205, v183
	v_sub_f32_e32 v183, v214, v236
	v_mfma_f32_16x16x32_bf16 v[40:43], v[84:87], v[206:209], v[40:43]
	v_sub_f32_e32 v204, v204, v236
	s_mov_b64 s[24:25], -1
	v_mfma_f32_16x16x32_bf16 v[36:39], v[88:91], v[206:209], v[36:39]
	v_mfma_f32_16x16x32_bf16 v[28:31], v[92:95], v[206:209], v[28:31]
	v_mov_b32_e32 v206, v226
	v_mov_b32_e32 v208, v225
	ds_read_b128 v[212:215], v228 offset:6144
	ds_read_b128 v[220:223], v228 offset:7168
	s_waitcnt lgkmcnt(1)
; __device__ __forceinline__ void attn_step(int ks, const KVB& b, int L16, int r, int i0, int iq, int lane,
;                                           const bf16x8* qs, f32x4 (&o)[4], float& mrun, float& lrun) {
;     ...
;   f32x4 sa = __builtin_amdgcn_mfma_f32_16x16x32_bf16(b.k0, qB0, z, 0, 0, 0);
;   sa = __builtin_amdgcn_mfma_f32_16x16x32_bf16(b.k1, qB1, sa, 0, 0, 0);
;   f32x4 sb = __builtin_amdgcn_mfma_f32_16x16x32_bf16(b.k2, qB0, z, 0, 0, 0);
;   sb = __builtin_amdgcn_mfma_f32_16x16x32_bf16(b.k3, qB1, sb, 0, 0, 0);
;   int jlo = max(iq - D + (cV < r ? 1 : 0), 0) - sV;
;   int jhi = min(iq + D - (cV > r ? 1 : 0), L16 - 1) - sV;
;   const float NINF = -__builtin_inff();
;   float s8[8];
;   float mt = -1e30f;
; #pragma unroll
;   for (int j = 0; j < 8; ++j) {
;     float sv = j < 4 ? sa[j] : sb[j - 4];
;     sv = (j >= jlo && j <= jhi) ? sv : NINF;
;     s8[j] = sv;
;     mt = fmaxf(mt, sv);
;   }
;   mt = fmaxf(mt, __shfl_xor(mt, 16));
;   mt = fmaxf(mt, __shfl_xor(mt, 32));
;   float mnew = fmaxf(mrun, mt);
;   float alpha = __builtin_amdgcn_exp2f(mrun - mnew);
;   mrun = mnew;
;   float ps = 0.f;
;   float p8[8];
; #pragma unroll
;   for (int j = 0; j < 8; ++j) { p8[j] = __builtin_amdgcn_exp2f(s8[j] - mnew); ps += p8[j]; }
;   lrun = lrun * alpha + ps;
;   union { uint4 u; bf16x8 v; } pb;
;   pb.u = make_uint4(pack2(p8[0], p8[1]), pack2(p8[2], p8[3]), pack2(p8[4], p8[5]), pack2(p8[6], p8[7]));
; #pragma unroll
;   for (int dt = 0; dt < 4; ++dt) { o[dt][0] *= alpha; o[dt][1] *= alpha; o[dt][2] *= alpha; o[dt][3] *= alpha; }
;   o[0] = __builtin_amdgcn_mfma_f32_16x16x32_bf16(b.v0, pb.v, o[0], 0, 0, 0);
;   o[1] = __builtin_amdgcn_mfma_f32_16x16x32_bf16(b.v1, pb.v, o[1], 0, 0, 0);
;   o[2] = __builtin_amdgcn_mfma_f32_16x16x32_bf16(b.v2, pb.v, o[2], 0, 0, 0);
;   o[3] = __builtin_amdgcn_mfma_f32_16x16x32_bf16(b.v3, pb.v, o[3], 0, 0, 0);
; template <int NT>
; __device__ void attn_unitN(const P& p, int u) {
;     ...
;   for (int ks = 0; ks < 18; ks += 2) {
; #pragma unroll
;     for (int t = 0; t < NT; ++t)
;       attn_step(ks, bA, L16, rb + RS * t, i0, iq, lane, qs + t * 128, o[t], mrun[t], lrun[t]);
;     bA = attn_load_e<NT>(ks + 2, kbase, vbase, L16, rb, i0, lane);
; #pragma unroll
;     for (int t = 0; t < NT; ++t)
;       attn_step(ks + 1, bB, L16, rb + RS * t, i0, iq, lane, qs + t * 128, o[t], mrun[t], lrun[t]);
	v_mfma_f32_16x16x32_bf16 v[108:111], v[108:111], v[212:215], 0
	s_add_i32 s5, s5, s23
	v_exp_f32_e32 v207, v183
	v_sub_f32_e32 v183, v216, v236
	s_waitcnt lgkmcnt(0)
	v_mfma_f32_16x16x32_bf16 v[104:107], v[104:107], v[220:223], v[108:111]
	v_exp_f32_e32 v209, v183
	v_sub_f32_e32 v183, v217, v236
	v_exp_f32_e32 v211, v183
	v_ashrrev_i32_e32 v108, 4, v206
	v_mfma_f32_16x16x32_bf16 v[100:103], v[100:103], v[212:215], 0
	v_add_u32_e32 v109, s22, v108
	v_lshlrev_b32_e32 v108, 2, v108
	v_and_or_b32 v108, s4, 3, v108
	v_cndmask_b32_e64 v108, v108, v109, s[0:1]
	v_mfma_f32_16x16x32_bf16 v[96:99], v[96:99], v[220:223], v[100:103]
	v_cmp_gt_i32_e32 vcc, s4, v108
	v_cmp_lt_i32_e64 s[0:1], s4, v108
	v_sub_f32_e32 v183, v210, v236
	v_add_u32_e32 v101, s61, v208
	v_addc_co_u32_e32 v100, vcc, v208, v218, vcc
	v_subbrev_co_u32_e64 v101, s[0:1], 0, v101, s[0:1]
	v_max_i32_e32 v100, 0, v100
	v_min_i32_e32 v101, s43, v101
	v_subrev_u32_e32 v100, s5, v100
	v_subrev_u32_e32 v101, s5, v101
	v_cmp_lt_i32_e32 vcc, 0, v100
	v_cmp_gt_i32_e64 s[0:1], 0, v101
	s_or_b64 vcc, vcc, s[0:1]
	v_cndmask_b32_e32 v102, v104, v219, vcc
	v_cmp_lt_i32_e32 vcc, 1, v100
	v_cmp_gt_i32_e64 s[0:1], 1, v101
	s_or_b64 vcc, vcc, s[0:1]
	v_cndmask_b32_e32 v103, v105, v219, vcc
	v_cmp_lt_i32_e32 vcc, 2, v100
	v_cmp_gt_i32_e64 s[0:1], 2, v101
	s_or_b64 vcc, vcc, s[0:1]
	v_cndmask_b32_e32 v105, v106, v219, vcc
	v_cmp_lt_i32_e32 vcc, 3, v100
	v_cmp_gt_i32_e64 s[0:1], 3, v101
	s_or_b64 vcc, vcc, s[0:1]
	v_cndmask_b32_e32 v106, v107, v219, vcc
	v_cmp_lt_i32_e32 vcc, 4, v100
	v_cmp_gt_i32_e64 s[0:1], 4, v101
	s_or_b64 vcc, vcc, s[0:1]
	v_cndmask_b32_e32 v96, v96, v219, vcc
	v_cmp_lt_i32_e32 vcc, 5, v100
	v_cmp_gt_i32_e64 s[0:1], 5, v101
	s_or_b64 vcc, vcc, s[0:1]
	v_cndmask_b32_e32 v97, v97, v219, vcc
	v_cmp_lt_i32_e32 vcc, 6, v100
	v_cmp_gt_i32_e64 s[0:1], 6, v101
	s_or_b64 vcc, vcc, s[0:1]
	v_max3_f32 v104, v102, s41, v103
	v_cndmask_b32_e32 v98, v98, v219, vcc
	v_cmp_lt_i32_e32 vcc, 7, v100
	v_cmp_gt_i32_e64 s[0:1], 7, v101
	v_max3_f32 v104, v104, v105, v106
	s_or_b64 vcc, vcc, s[0:1]
	v_max3_f32 v104, v104, v96, v97
	v_cndmask_b32_e32 v100, v99, v219, vcc
	v_max3_f32 v99, v104, v98, v100
	v_mov_b32_e32 v101, v99
	v_mov_b32_e32 v245, v99
	s_nop 1
	v_permlane16_swap_b32_e32 v101, v245
	v_max_f32_e32 v101, v101, v245
	v_sub_f32_e32 v104, v235, v236
	v_exp_f32_e32 v215, v104
	v_sub_f32_e32 v104, v242, v236
	v_exp_f32_e32 v218, v204
	s_waitcnt lgkmcnt(0)
	v_max_f32_e32 v101, v101, v101
	v_max_f32_e32 v99, v99, v101
	v_mov_b32_e32 v101, v99
	v_mov_b32_e32 v245, v99
	s_nop 1
	v_permlane32_swap_b32_e32 v101, v245
	v_max_f32_e32 v101, v101, v245
	v_exp_f32_e32 v217, v104
	v_sub_f32_e32 v104, v165, v236
	v_exp_f32_e32 v213, v183
	v_exp_f32_e32 v221, v104
	s_waitcnt lgkmcnt(0)
	v_max3_f32 v235, v203, v99, v101
	v_sub_f32_e32 v99, v102, v235
	v_exp_f32_e32 v204, v99
	v_sub_f32_e32 v99, v103, v235
	v_sub_f32_e32 v96, v96, v235
	v_exp_f32_e32 v206, v99
	v_sub_f32_e32 v99, v105, v235
	v_exp_f32_e32 v212, v96
	v_sub_f32_e32 v96, v97, v235
	v_sub_f32_e32 v101, v203, v235
	v_exp_f32_e32 v208, v99
	v_sub_f32_e32 v99, v106, v235
	v_exp_f32_e32 v214, v96
	v_sub_f32_e32 v96, v98, v235
	v_sub_f32_e32 v100, v100, v235
	s_and_b32 s0, s59, 12
	v_exp_f32_e32 v210, v99
	v_exp_f32_e32 v216, v96
	v_exp_f32_e32 v220, v100
	v_exp_f32_e32 v222, v101
	s_add_i32 s22, s60, 3
	s_xor_b32 s23, s0, 8
	s_cmp_gt_u32 s60, 14
	s_cselect_b64 s[4:5], -1, 0
	v_pk_mul_f32 v[34:35], v[34:35], v[218:219] op_sel_hi:[1,0]
	v_pk_mul_f32 v[32:33], v[32:33], v[218:219] op_sel_hi:[1,0]
	v_cvt_pk_bf16_f32 v96, v205, v207
	v_cvt_pk_bf16_f32 v97, v209, v211
	v_cvt_pk_bf16_f32 v98, v213, v215
	v_cvt_pk_bf16_f32 v99, v217, v221
	v_pk_mul_f32 v[26:27], v[26:27], v[218:219] op_sel_hi:[1,0]
	v_pk_mul_f32 v[24:25], v[24:25], v[218:219] op_sel_hi:[1,0]
	v_pk_mul_f32 v[22:23], v[22:23], v[218:219] op_sel_hi:[1,0]
	v_pk_mul_f32 v[20:21], v[20:21], v[218:219] op_sel_hi:[1,0]
	v_pk_mul_f32 v[14:15], v[14:15], v[218:219] op_sel_hi:[1,0]
	v_pk_mul_f32 v[12:13], v[12:13], v[218:219] op_sel_hi:[1,0]
	s_and_b64 s[0:1], s[4:5], exec
	v_mfma_f32_16x16x32_bf16 v[32:35], v[80:83], v[96:99], v[32:35]
	v_mul_f32_e64 v18, v18, v222
	v_mul_f32_e64 v19, v19, v222
	v_pk_mul_f32 v[16:17], v[16:17], v[222:223] op_sel_hi:[1,0]
	v_pk_mul_f32 v[10:11], v[10:11], v[222:223] op_sel_hi:[1,0]
	v_mfma_f32_16x16x32_bf16 v[24:27], v[84:87], v[96:99], v[24:27]
	v_mul_f32_e64 v8, v8, v222
	v_mul_f32_e64 v9, v9, v222
	v_pk_mul_f32 v[6:7], v[6:7], v[222:223] op_sel_hi:[1,0]
	v_pk_mul_f32 v[4:5], v[4:5], v[222:223] op_sel_hi:[1,0]
	v_mfma_f32_16x16x32_bf16 v[20:23], v[88:91], v[96:99], v[20:23]
	v_mul_f32_e64 v2, v2, v222
	v_mul_f32_e64 v3, v3, v222
	v_pk_mul_f32 v[0:1], v[0:1], v[222:223] op_sel_hi:[1,0]
	s_cselect_b32 s63, s23, 0
	v_mfma_f32_16x16x32_bf16 v[12:15], v[92:95], v[96:99], v[12:15]
	v_cvt_pk_bf16_f32 v96, v204, v206
	v_cvt_pk_bf16_f32 v97, v208, v210
	v_cvt_pk_bf16_f32 v98, v212, v214
	v_cvt_pk_bf16_f32 v99, v216, v220
	s_add_i32 s63, s63, s42
	s_min_u32 s61, s22, 18
	v_mfma_f32_16x16x32_bf16 v[16:19], v[80:83], v[96:99], v[16:19]
	s_cmp_gt_u32 s60, 8
	s_cselect_b64 s[22:23], -1, 0
	s_and_b64 vcc, exec, s[22:23]
	v_mfma_f32_16x16x32_bf16 v[8:11], v[84:87], v[96:99], v[8:11]
	v_mfma_f32_16x16x32_bf16 v[4:7], v[88:91], v[96:99], v[4:7]
	v_mfma_f32_16x16x32_bf16 v[0:3], v[92:95], v[96:99], v[0:3]
	s_cbranch_vccz .LBB0_254
	s_mov_b64 vcc, s[0:1]
	s_cbranch_vccz .LBB0_251
	v_lshl_add_u32 v80, s61, 5, v231
	s_mov_b64 s[24:25], 0

; __device__ __forceinline__ KVB attn_load(int ks, const u16* __restrict__ kbase, const u16* __restrict__ vbase, int L16,
;                                          int r, int i0, int lane) {
;   KVB b;
;   const int quad = lane >> 4, l15 = lane & 15, gk = l15 >> 2, ek = l15 & 3;
;   int cK, sK; attn_desc(ks, gk, r, i0, cK, sK);
;   int ia = sK + ek, ib = ia + 4;
;   ia = min(max(ia, 0), L16 - 1); ib = min(max(ib, 0), L16 - 1);
;   const u16* ka = kbase + (size_t)(cK + 16 * ia) * 512;
;   const u16* kb = kbase + (size_t)(cK + 16 * ib) * 512;
;   b.k0 = *(const bf16x8*)ka; b.k1 = *(const bf16x8*)(ka + 8);
;   b.k2 = *(const bf16x8*)kb; b.k3 = *(const bf16x8*)(kb + 8);
;   int cV, sV; attn_desc(ks, quad, r, i0, cV, sV);
;   const u16* vp = vbase + ((ptrdiff_t)cV * (L16 >> 2) + (sV >> 2)) * 256 + l15 * 4;
;   {
;     union { struct { uint2 a, b; } p; bf16x8 v; } c0, c1, c2, c3;
;     c0.p.a = *(const uint2*)(vp);        c0.p.b = *(const uint2*)(vp + 256);
;     c1.p.a = *(const uint2*)(vp + 64);   c1.p.b = *(const uint2*)(vp + 64 + 256);
;     c2.p.a = *(const uint2*)(vp + 128);  c2.p.b = *(const uint2*)(vp + 128 + 256);
;     c3.p.a = *(const uint2*)(vp + 192);  c3.p.b = *(const uint2*)(vp + 192 + 256);
;     b.v0 = c0.v; b.v1 = c1.v; b.v2 = c2.v; b.v3 = c3.v;
;   }
;   return b;
; template <int NT>
; __device__ void attn_unitN(const P& p, int u) {
;     ...
;   for (int kk = 0; kk < 5; ++kk) {
;     int e0 = 18 + NT * kk, ks = 18 + kk;
; #pragma unroll
;     for (int t = 0; t < NT; t += 2) {
;       attn_step(ks, bA, L16, rb + RS * t, i0, iq, lane, qs + t * 128, o[t], mrun[t], lrun[t]);
;       { int f = min(e0 + t + 2, EMAX) - 18;
;         bA = attn_load(18 + f / NT, kbase, vbase, L16, rb + RS * (f % NT), i0, lane); }
;       attn_step(ks, bB, L16, rb + RS * (t + 1), i0, iq, lane, qs + (t + 1) * 128, o[t + 1], mrun[t + 1], lrun[t + 1]);
;       { int f = min(e0 + t + 3, EMAX) - 18;
;         bB = attn_load(18 + f / NT, kbase, vbase, L16, rb + RS * (f % NT), i0, lane); }
;     }
.LBB0_267:
	v_mov_b32_e32 v136, v226
	v_mov_b32_e32 v137, v225
	s_mov_b32 s0, s42
	s_mov_b32 s1, s46
	ds_read_b128 v[128:131], v228
	ds_read_b128 v[132:135], v228 offset:1024
	s_waitcnt vmcnt(21) lgkmcnt(1)
	v_mfma_f32_16x16x32_bf16 v[116:119], v[116:119], v[128:131], 0
	v_ashrrev_i32_e32 v136, 4, v136
	s_sub_i32 s0, s1, 64
	v_add_u32_e32 v136, s11, v136
	v_mfma_f32_16x16x32_bf16 v[124:127], v[124:127], v[128:131], 0
	v_lshl_add_u32 v136, v136, 3, s0
	v_ashrrev_i32_e32 v192, 2, v180
	v_ashrrev_i32_e32 v193, 31, v192
	s_waitcnt vmcnt(20) lgkmcnt(0)
	v_mfma_f32_16x16x32_bf16 v[112:115], v[112:115], v[132:135], v[116:119]
	v_lshl_add_u64 v[128:129], s[4:5], 0, v[192:193]
	v_lshlrev_b64 v[128:129], 9, v[128:129]
	v_mov_b32_e32 v162, v225
	v_subrev_u32_e32 v116, 64, v137
	v_add_u32_e32 v117, 64, v137
	v_mfma_f32_16x16x32_bf16 v[120:123], v[120:123], v[132:135], v[124:127]
	v_max_i32_e32 v116, 0, v116
	v_min_i32_e32 v117, s43, v117
	v_sub_u32_e32 v116, v116, v136
	v_sub_u32_e32 v117, v117, v136
	v_cmp_lt_i32_e32 vcc, 0, v116
	v_cmp_gt_i32_e64 s[0:1], 0, v117
	s_or_b64 vcc, vcc, s[0:1]
	s_nop 0
	v_cndmask_b32_e32 v118, v120, v219, vcc
	v_cmp_lt_i32_e32 vcc, 1, v116
	v_cmp_gt_i32_e64 s[0:1], 1, v117
	s_or_b64 vcc, vcc, s[0:1]
	v_cndmask_b32_e32 v119, v121, v219, vcc
	v_cmp_lt_i32_e32 vcc, 2, v116
	v_cmp_gt_i32_e64 s[0:1], 2, v117
	s_or_b64 vcc, vcc, s[0:1]
	v_cndmask_b32_e32 v121, v122, v219, vcc
	v_cmp_lt_i32_e32 vcc, 3, v116
	v_cmp_gt_i32_e64 s[0:1], 3, v117
	s_or_b64 vcc, vcc, s[0:1]
	v_cndmask_b32_e32 v122, v123, v219, vcc
	v_cmp_lt_i32_e32 vcc, 4, v116
	v_cmp_gt_i32_e64 s[0:1], 4, v117
	s_or_b64 vcc, vcc, s[0:1]
	v_cndmask_b32_e32 v112, v112, v219, vcc
	v_cmp_lt_i32_e32 vcc, 5, v116
	v_cmp_gt_i32_e64 s[0:1], 5, v117
	s_or_b64 vcc, vcc, s[0:1]
	v_cndmask_b32_e32 v113, v113, v219, vcc
	v_cmp_lt_i32_e32 vcc, 6, v116
	v_cmp_gt_i32_e64 s[0:1], 6, v117
	s_or_b64 vcc, vcc, s[0:1]
	v_max3_f32 v120, v118, s41, v119
	v_cndmask_b32_e32 v114, v114, v219, vcc
	v_cmp_lt_i32_e32 vcc, 7, v116
	v_cmp_gt_i32_e64 s[0:1], 7, v117
	v_max3_f32 v120, v120, v121, v122
	s_or_b64 vcc, vcc, s[0:1]
	v_max3_f32 v120, v120, v112, v113
	v_cndmask_b32_e32 v115, v115, v219, vcc
	v_max3_f32 v116, v120, v114, v115
	v_mov_b32_e32 v117, v116
	v_mov_b32_e32 v245, v116
	s_nop 1
	v_permlane16_swap_b32_e32 v117, v245
	v_max_f32_e32 v117, v117, v245
	s_mov_b32 s0, s56
	s_mov_b32 s1, s46
	s_add_i32 s22, s11, 20
	v_add_u32_e32 v180, 32, v180
	s_waitcnt lgkmcnt(0)
	v_max_f32_e32 v117, v117, v117
	v_max_f32_e32 v116, v116, v117
	v_mov_b32_e32 v117, v116
	v_mov_b32_e32 v245, v116
	s_nop 1
	v_permlane32_swap_b32_e32 v117, v245
	v_max_f32_e32 v117, v117, v245
	s_waitcnt lgkmcnt(0)
	v_max3_f32 v182, v143, v116, v117
	v_sub_f32_e32 v112, v112, v182
	v_exp_f32_e32 v171, v112
	v_sub_f32_e32 v112, v113, v182
	v_exp_f32_e32 v173, v112
	v_sub_f32_e32 v112, v114, v182
	v_exp_f32_e32 v175, v112
	v_sub_f32_e32 v112, v115, v182
	v_exp_f32_e32 v177, v112
	v_max_i32_e32 v112, 0, v181
	v_max_i32_e32 v113, -4, v181
	v_sub_f32_e32 v117, v118, v182
	v_min_i32_e32 v112, s43, v112
	v_add_u32_e32 v113, 4, v113
	v_exp_f32_e32 v163, v117
	v_sub_f32_e32 v117, v119, v182
	v_min_u32_e32 v114, s43, v113
	v_lshlrev_b32_e32 v194, 4, v112
	v_exp_f32_e32 v165, v117
	v_sub_f32_e32 v117, v121, v182
	v_add_u32_e32 v144, s8, v194
	v_lshlrev_b32_e32 v195, 4, v114
	v_sub_f32_e32 v116, v143, v182
	v_exp_f32_e32 v167, v117
	v_sub_f32_e32 v117, v122, v182
	v_lshrrev_b32_e32 v243, 8, v144
	v_and_b32_e32 v244, 15, v144
	v_lshlrev_b32_e32 v243, 18, v243
	v_lshl_or_b32 v243, v244, 11, v243
	v_bfe_u32 v244, v144, 6, 2
	v_lshl_or_b32 v243, v244, 9, v243
	v_bfe_u32 v244, v144, 4, 2
	v_lshl_or_b32 v112, v244, 5, v243
	v_mov_b32_e32 v113, 0
	v_add_u32_e32 v144, s8, v195
	v_exp_f32_e32 v169, v117
	v_exp_f32_e32 v179, v116
	v_lshl_add_u64 v[116:117], v[154:155], 0, v[112:113]
	v_lshrrev_b32_e32 v243, 8, v144
	v_and_b32_e32 v244, 15, v144
	v_lshlrev_b32_e32 v243, 18, v243
	v_lshl_or_b32 v243, v244, 11, v243
	v_bfe_u32 v244, v144, 6, 2
	v_lshl_or_b32 v243, v244, 9, v243
	v_bfe_u32 v244, v144, 4, 2
	v_lshl_or_b32 v112, v244, 5, v243
	v_mov_b32_e32 v113, 0
	v_lshl_add_u64 v[124:125], v[154:155], 0, v[112:113]
	global_load_dwordx4 v[112:115], v[116:117], off
	s_nop 0
	global_load_dwordx4 v[116:119], v[116:117], off offset:16
	s_nop 0
	global_load_dwordx4 v[120:123], v[124:125], off
	s_nop 0
	global_load_dwordx4 v[124:127], v[124:125], off offset:16
	v_lshl_add_u64 v[142:143], v[158:159], 0, v[128:129]
	v_mov_b32_e32 v144, v226
	global_load_dwordx2 v[128:129], v[142:143], off
	global_load_dwordx2 v[130:131], v[142:143], off offset:512
	global_load_dwordx2 v[132:133], v[142:143], off offset:128
	global_load_dwordx2 v[134:135], v[142:143], off offset:640
	global_load_dwordx2 v[136:137], v[142:143], off offset:256
	global_load_dwordx2 v[138:139], v[142:143], off offset:768
	global_load_dwordx2 v[140:141], v[142:143], off offset:384
	s_nop 0
	global_load_dwordx2 v[142:143], v[142:143], off offset:896
	ds_read_b128 v[184:187], v228 offset:2048
	ds_read_b128 v[188:191], v228 offset:3072
	s_waitcnt vmcnt(21) lgkmcnt(1)
	v_mfma_f32_16x16x32_bf16 v[100:103], v[100:103], v[184:187], 0
	v_ashrrev_i32_e32 v144, 4, v144
	s_sub_i32 s0, s1, 64
	v_add_u32_e32 v144, s11, v144
	v_mfma_f32_16x16x32_bf16 v[108:111], v[108:111], v[184:187], 0
	v_lshl_add_u32 v144, v144, 3, s0
	v_add_u32_e32 v181, 32, v181
	s_waitcnt vmcnt(20) lgkmcnt(0)
; __device__ __forceinline__ void attn_step(int ks, const KVB& b, int L16, int r, int i0, int iq, int lane,
;                                           const bf16x8* qs, f32x4 (&o)[4], float& mrun, float& lrun) {
;     ...
;   f32x4 sa = __builtin_amdgcn_mfma_f32_16x16x32_bf16(b.k0, qB0, z, 0, 0, 0);
;   sa = __builtin_amdgcn_mfma_f32_16x16x32_bf16(b.k1, qB1, sa, 0, 0, 0);
;   f32x4 sb = __builtin_amdgcn_mfma_f32_16x16x32_bf16(b.k2, qB0, z, 0, 0, 0);
;   sb = __builtin_amdgcn_mfma_f32_16x16x32_bf16(b.k3, qB1, sb, 0, 0, 0);
;   int jlo = max(iq - D + (cV < r ? 1 : 0), 0) - sV;
;   int jhi = min(iq + D - (cV > r ? 1 : 0), L16 - 1) - sV;
;   const float NINF = -__builtin_inff();
;   float s8[8];
;   float mt = -1e30f;
; #pragma unroll
;   for (int j = 0; j < 8; ++j) {
;     float sv = j < 4 ? sa[j] : sb[j - 4];
;     sv = (j >= jlo && j <= jhi) ? sv : NINF;
;     s8[j] = sv;
;     mt = fmaxf(mt, sv);
;   }
;   mt = fmaxf(mt, __shfl_xor(mt, 16));
;   mt = fmaxf(mt, __shfl_xor(mt, 32));
;   float mnew = fmaxf(mrun, mt);
;   float alpha = __builtin_amdgcn_exp2f(mrun - mnew);
;   mrun = mnew;
;   float ps = 0.f;
;   float p8[8];
; #pragma unroll
;   for (int j = 0; j < 8; ++j) { p8[j] = __builtin_amdgcn_exp2f(s8[j] - mnew); ps += p8[j]; }
;   lrun = lrun * alpha + ps;
;   union { uint4 u; bf16x8 v; } pb;
;   pb.u = make_uint4(pack2(p8[0], p8[1]), pack2(p8[2], p8[3]), pack2(p8[4], p8[5]), pack2(p8[6], p8[7]));
; #pragma unroll
;   for (int dt = 0; dt < 4; ++dt) { o[dt][0] *= alpha; o[dt][1] *= alpha; o[dt][2] *= alpha; o[dt][3] *= alpha; }
;   o[0] = __builtin_amdgcn_mfma_f32_16x16x32_bf16(b.v0, pb.v, o[0], 0, 0, 0);
;   o[1] = __builtin_amdgcn_mfma_f32_16x16x32_bf16(b.v1, pb.v, o[1], 0, 0, 0);
;   o[2] = __builtin_amdgcn_mfma_f32_16x16x32_bf16(b.v2, pb.v, o[2], 0, 0, 0);
;   o[3] = __builtin_amdgcn_mfma_f32_16x16x32_bf16(b.v3, pb.v, o[3], 0, 0, 0);
	v_mfma_f32_16x16x32_bf16 v[96:99], v[96:99], v[188:191], v[100:103]
	s_nop 2
	v_subrev_u32_e32 v100, 64, v162
	v_add_u32_e32 v101, 64, v162
	v_mfma_f32_16x16x32_bf16 v[104:107], v[104:107], v[188:191], v[108:111]
	v_max_i32_e32 v100, 0, v100
	v_min_i32_e32 v101, s43, v101
	v_sub_u32_e32 v100, v100, v144
	v_sub_u32_e32 v101, v101, v144
	v_cmp_lt_i32_e32 vcc, 0, v100
	v_cmp_gt_i32_e64 s[0:1], 0, v101
	s_or_b64 vcc, vcc, s[0:1]
	s_nop 0
	v_cndmask_b32_e32 v102, v104, v219, vcc
	v_cmp_lt_i32_e32 vcc, 1, v100
	v_cmp_gt_i32_e64 s[0:1], 1, v101
	s_or_b64 vcc, vcc, s[0:1]
	v_cndmask_b32_e32 v103, v105, v219, vcc
	v_cmp_lt_i32_e32 vcc, 2, v100
	v_cmp_gt_i32_e64 s[0:1], 2, v101
	s_or_b64 vcc, vcc, s[0:1]
	v_cndmask_b32_e32 v105, v106, v219, vcc
	v_cmp_lt_i32_e32 vcc, 3, v100
	v_cmp_gt_i32_e64 s[0:1], 3, v101
	s_or_b64 vcc, vcc, s[0:1]
	v_cndmask_b32_e32 v106, v107, v219, vcc
	v_cmp_lt_i32_e32 vcc, 4, v100
	v_cmp_gt_i32_e64 s[0:1], 4, v101
	s_or_b64 vcc, vcc, s[0:1]
	v_cndmask_b32_e32 v96, v96, v219, vcc
	v_cmp_lt_i32_e32 vcc, 5, v100
	v_cmp_gt_i32_e64 s[0:1], 5, v101
	s_or_b64 vcc, vcc, s[0:1]
	v_cndmask_b32_e32 v97, v97, v219, vcc
	v_cmp_lt_i32_e32 vcc, 6, v100
	v_cmp_gt_i32_e64 s[0:1], 6, v101
	s_or_b64 vcc, vcc, s[0:1]
	v_max3_f32 v104, v102, s41, v103
	v_cndmask_b32_e32 v98, v98, v219, vcc
	v_cmp_lt_i32_e32 vcc, 7, v100
	v_cmp_gt_i32_e64 s[0:1], 7, v101
	v_max3_f32 v104, v104, v105, v106
	s_or_b64 vcc, vcc, s[0:1]
	v_max3_f32 v104, v104, v96, v97
	v_cndmask_b32_e32 v99, v99, v219, vcc
	v_max3_f32 v100, v104, v98, v99
	v_mov_b32_e32 v101, v100
	v_mov_b32_e32 v245, v100
	s_nop 1
	v_permlane16_swap_b32_e32 v101, v245
	v_max_f32_e32 v101, v101, v245
	v_add_u32_e32 v144, s10, v194
	s_mov_b32 s0, s8
	s_mov_b32 s1, s46
	s_waitcnt lgkmcnt(0)
	v_max_f32_e32 v101, v101, v101
	v_max_f32_e32 v100, v100, v101
	v_mov_b32_e32 v101, v100
	v_mov_b32_e32 v245, v100
	s_nop 1
	v_permlane32_swap_b32_e32 v101, v245
	v_max_f32_e32 v101, v101, v245
	s_waitcnt lgkmcnt(0)
	v_max3_f32 v183, v237, v100, v101
	v_sub_f32_e32 v101, v102, v183
	v_exp_f32_e32 v162, v101
	v_sub_f32_e32 v101, v103, v183
	v_sub_f32_e32 v96, v96, v183
	v_exp_f32_e32 v164, v101
	v_sub_f32_e32 v101, v105, v183
	v_exp_f32_e32 v170, v96
	v_sub_f32_e32 v96, v97, v183
	v_exp_f32_e32 v166, v101
	v_sub_f32_e32 v101, v106, v183
	v_exp_f32_e32 v172, v96
	v_sub_f32_e32 v96, v98, v183
	v_exp_f32_e32 v168, v101
	v_exp_f32_e32 v174, v96
	v_sub_f32_e32 v96, v99, v183
	v_exp_f32_e32 v176, v96
	v_pk_add_f32 v[96:97], v[162:163], 0 op_sel_hi:[1,0]
	v_sub_f32_e32 v100, v237, v183
	v_pk_add_f32 v[96:97], v[164:165], v[96:97]
	v_exp_f32_e32 v178, v100
	v_pk_add_f32 v[96:97], v[166:167], v[96:97]
	v_cvt_pk_bf16_f32 v98, v171, v173
	v_pk_add_f32 v[96:97], v[168:169], v[96:97]
	v_cvt_pk_bf16_f32 v99, v175, v177
	v_pk_add_f32 v[96:97], v[170:171], v[96:97]
	v_pk_mul_f32 v[50:51], v[50:51], v[178:179] op_sel_hi:[1,0]
	v_pk_add_f32 v[96:97], v[172:173], v[96:97]
	v_pk_mul_f32 v[48:49], v[48:49], v[178:179] op_sel_hi:[1,0]
	v_pk_add_f32 v[96:97], v[174:175], v[96:97]
	v_pk_mul_f32 v[42:43], v[42:43], v[178:179] op_sel_hi:[1,0]
	v_pk_add_f32 v[100:101], v[176:177], v[96:97]
	v_mov_b32_e32 v96, v179
	v_pk_mul_f32 v[62:63], v[62:63], v[96:97] op_sel_hi:[1,0]
	v_pk_mul_f32 v[60:61], v[60:61], v[96:97] op_sel_hi:[1,0]
	v_pk_mul_f32 v[58:59], v[58:59], v[96:97] op_sel_hi:[1,0]
	v_pk_mul_f32 v[56:57], v[56:57], v[96:97] op_sel_hi:[1,0]
	v_pk_mul_f32 v[54:55], v[54:55], v[96:97] op_sel_hi:[1,0]
	v_pk_mul_f32 v[52:53], v[52:53], v[96:97] op_sel_hi:[1,0]
	v_pk_mul_f32 v[46:47], v[46:47], v[96:97] op_sel_hi:[1,0]
	v_pk_mul_f32 v[44:45], v[44:45], v[96:97] op_sel_hi:[1,0]
	v_cvt_pk_bf16_f32 v96, v163, v165
	v_cvt_pk_bf16_f32 v97, v167, v169
	v_pk_mul_f32 v[40:41], v[40:41], v[178:179] op_sel_hi:[1,0]
	v_pk_mul_f32 v[38:39], v[38:39], v[178:179] op_sel_hi:[1,0]
	v_mfma_f32_16x16x32_bf16 v[60:63], v[64:67], v[96:99], v[60:63]
	v_mul_f32_e64 v36, v36, v178
	v_mul_f32_e64 v37, v37, v178
	v_pk_mul_f32 v[30:31], v[30:31], v[178:179] op_sel_hi:[1,0]
	v_pk_mul_f32 v[28:29], v[28:29], v[178:179] op_sel_hi:[1,0]
	v_cvt_pk_bf16_f32 v64, v162, v164
	v_cvt_pk_bf16_f32 v65, v166, v168
	v_cvt_pk_bf16_f32 v66, v170, v172
	v_cvt_pk_bf16_f32 v67, v174, v176
	v_mfma_f32_16x16x32_bf16 v[56:59], v[68:71], v[96:99], v[56:59]
	v_fma_f32 v160, v160, v178, v100
	v_fma_f32 v161, v161, v179, v101
	v_mov_b32_e32 v162, v226
	v_mov_b32_e32 v164, v225
	s_waitcnt vmcnt(15)
	v_mfma_f32_16x16x32_bf16 v[48:51], v[80:83], v[64:67], v[48:51]
	v_mov_b32_e32 v237, v183
	s_waitcnt vmcnt(14)
	v_mfma_f32_16x16x32_bf16 v[40:43], v[84:87], v[64:67], v[40:43]
	s_waitcnt vmcnt(13)
	v_mfma_f32_16x16x32_bf16 v[36:39], v[88:91], v[64:67], v[36:39]
	s_waitcnt vmcnt(12)
; __device__ __forceinline__ KVB attn_load(int ks, const u16* __restrict__ kbase, const u16* __restrict__ vbase, int L16,
;                                          int r, int i0, int lane) {
;   KVB b;
;   const int quad = lane >> 4, l15 = lane & 15, gk = l15 >> 2, ek = l15 & 3;
;   int cK, sK; attn_desc(ks, gk, r, i0, cK, sK);
;   int ia = sK + ek, ib = ia + 4;
;   ia = min(max(ia, 0), L16 - 1); ib = min(max(ib, 0), L16 - 1);
;   const u16* ka = kbase + (size_t)(cK + 16 * ia) * 512;
; __device__ __forceinline__ void attn_step(int ks, const KVB& b, int L16, int r, int i0, int iq, int lane,
;                                           const bf16x8* qs, f32x4 (&o)[4], float& mrun, float& lrun) {
;     ...
;   f32x4 sa = __builtin_amdgcn_mfma_f32_16x16x32_bf16(b.k0, qB0, z, 0, 0, 0);
;   sa = __builtin_amdgcn_mfma_f32_16x16x32_bf16(b.k1, qB1, sa, 0, 0, 0);
;   f32x4 sb = __builtin_amdgcn_mfma_f32_16x16x32_bf16(b.k2, qB0, z, 0, 0, 0);
;   sb = __builtin_amdgcn_mfma_f32_16x16x32_bf16(b.k3, qB1, sb, 0, 0, 0);
;   int jlo = max(iq - D + (cV < r ? 1 : 0), 0) - sV;
;   int jhi = min(iq + D - (cV > r ? 1 : 0), L16 - 1) - sV;
;   const float NINF = -__builtin_inff();
;   float s8[8];
;   float mt = -1e30f;
; #pragma unroll
;   for (int j = 0; j < 8; ++j) {
;     float sv = j < 4 ? sa[j] : sb[j - 4];
;     sv = (j >= jlo && j <= jhi) ? sv : NINF;
;     s8[j] = sv;
;     mt = fmaxf(mt, sv);
;   }
;   mt = fmaxf(mt, __shfl_xor(mt, 16));
;   mt = fmaxf(mt, __shfl_xor(mt, 32));
;   float mnew = fmaxf(mrun, mt);
;   float alpha = __builtin_amdgcn_exp2f(mrun - mnew);
;   mrun = mnew;
;   float ps = 0.f;
;   float p8[8];
; #pragma unroll
;   for (int j = 0; j < 8; ++j) { p8[j] = __builtin_amdgcn_exp2f(s8[j] - mnew); ps += p8[j]; }
;   lrun = lrun * alpha + ps;
;   union { uint4 u; bf16x8 v; } pb;
;   pb.u = make_uint4(pack2(p8[0], p8[1]), pack2(p8[2], p8[3]), pack2(p8[4], p8[5]), pack2(p8[6], p8[7]));
; #pragma unroll
;   for (int dt = 0; dt < 4; ++dt) { o[dt][0] *= alpha; o[dt][1] *= alpha; o[dt][2] *= alpha; o[dt][3] *= alpha; }
;   o[0] = __builtin_amdgcn_mfma_f32_16x16x32_bf16(b.v0, pb.v, o[0], 0, 0, 0);
;   o[1] = __builtin_amdgcn_mfma_f32_16x16x32_bf16(b.v1, pb.v, o[1], 0, 0, 0);
;   o[2] = __builtin_amdgcn_mfma_f32_16x16x32_bf16(b.v2, pb.v, o[2], 0, 0, 0);
;   o[3] = __builtin_amdgcn_mfma_f32_16x16x32_bf16(b.v3, pb.v, o[3], 0, 0, 0);
	v_mfma_f32_16x16x32_bf16 v[28:31], v[92:95], v[64:67], v[28:31]
	v_lshrrev_b32_e32 v243, 8, v144
	v_and_b32_e32 v244, 15, v144
	v_lshlrev_b32_e32 v243, 18, v243
	v_lshl_or_b32 v243, v244, 11, v243
	v_bfe_u32 v244, v144, 6, 2
	v_lshl_or_b32 v243, v244, 9, v243
	v_bfe_u32 v244, v144, 4, 2
	v_lshl_or_b32 v64, v244, 5, v243
	v_mov_b32_e32 v65, 0
	v_add_u32_e32 v144, s10, v195
	v_lshl_add_u64 v[64:65], v[154:155], 0, v[64:65]
	v_lshrrev_b32_e32 v243, 8, v144
	v_and_b32_e32 v244, 15, v144
	v_lshlrev_b32_e32 v243, 18, v243
	v_lshl_or_b32 v243, v244, 11, v243
	v_bfe_u32 v244, v144, 6, 2
	v_lshl_or_b32 v243, v244, 9, v243
	v_bfe_u32 v244, v144, 4, 2
	v_lshl_or_b32 v66, v244, 5, v243
	v_mov_b32_e32 v67, 0
	v_mfma_f32_16x16x32_bf16 v[52:55], v[72:75], v[96:99], v[52:55]
	v_lshl_add_u64 v[66:67], v[154:155], 0, v[66:67]
	v_mov_b32_e32 v72, v226
	v_mfma_f32_16x16x32_bf16 v[44:47], v[76:79], v[96:99], v[44:47]
	global_load_dwordx4 v[96:99], v[64:65], off
	global_load_dwordx4 v[100:103], v[64:65], off offset:16
	global_load_dwordx4 v[104:107], v[66:67], off
	global_load_dwordx4 v[108:111], v[66:67], off offset:16
	v_lshl_add_u64 v[64:65], s[20:21], 0, v[192:193]
	v_lshlrev_b64 v[64:65], 9, v[64:65]
	v_lshl_add_u64 v[64:65], v[158:159], 0, v[64:65]
	v_mov_b32_e32 v76, v225
	global_load_dwordx2 v[80:81], v[64:65], off
	global_load_dwordx2 v[82:83], v[64:65], off offset:512
	global_load_dwordx2 v[84:85], v[64:65], off offset:128
	global_load_dwordx2 v[86:87], v[64:65], off offset:640
	global_load_dwordx2 v[88:89], v[64:65], off offset:256
	global_load_dwordx2 v[90:91], v[64:65], off offset:768
	global_load_dwordx2 v[92:93], v[64:65], off offset:384
	global_load_dwordx2 v[94:95], v[64:65], off offset:896
	ds_read_b128 v[64:67], v228 offset:4096
	ds_read_b128 v[68:71], v228 offset:5120
	v_ashrrev_i32_e32 v72, 4, v72
	s_sub_i32 s0, s1, 64
	v_add_u32_e32 v72, s11, v72
	v_lshl_add_u32 v77, v72, 3, s0
	s_waitcnt vmcnt(23) lgkmcnt(1)
	v_mfma_f32_16x16x32_bf16 v[72:75], v[112:115], v[64:67], 0
	s_waitcnt vmcnt(21)
	v_mfma_f32_16x16x32_bf16 v[64:67], v[120:123], v[64:67], 0
	s_waitcnt lgkmcnt(0)
	v_mfma_f32_16x16x32_bf16 v[72:75], v[116:119], v[68:71], v[72:75]
	s_waitcnt vmcnt(20)
	v_mfma_f32_16x16x32_bf16 v[64:67], v[124:127], v[68:71], v[64:67]
	v_subrev_u32_e32 v68, 64, v76
	v_add_u32_e32 v69, 64, v76
	v_max_i32_e32 v68, 0, v68
	v_min_i32_e32 v69, s43, v69
	v_sub_u32_e32 v68, v68, v77
	v_sub_u32_e32 v69, v69, v77
	v_cmp_lt_i32_e32 vcc, 0, v68
	v_cmp_gt_i32_e64 s[0:1], 0, v69
	s_or_b64 vcc, vcc, s[0:1]
	v_cndmask_b32_e32 v70, v72, v219, vcc
	v_cmp_lt_i32_e32 vcc, 1, v68
	v_cmp_gt_i32_e64 s[0:1], 1, v69
	s_or_b64 vcc, vcc, s[0:1]
	v_cndmask_b32_e32 v71, v73, v219, vcc
	v_cmp_lt_i32_e32 vcc, 2, v68
	v_cmp_gt_i32_e64 s[0:1], 2, v69
	s_or_b64 vcc, vcc, s[0:1]
	v_cndmask_b32_e32 v73, v74, v219, vcc
	v_cmp_lt_i32_e32 vcc, 3, v68
	v_cmp_gt_i32_e64 s[0:1], 3, v69
	s_or_b64 vcc, vcc, s[0:1]
	v_cndmask_b32_e32 v74, v75, v219, vcc
	v_cmp_lt_i32_e32 vcc, 4, v68
	v_cmp_gt_i32_e64 s[0:1], 4, v69
	s_or_b64 vcc, vcc, s[0:1]
	v_cndmask_b32_e32 v64, v64, v219, vcc
	v_cmp_lt_i32_e32 vcc, 5, v68
	v_cmp_gt_i32_e64 s[0:1], 5, v69
	s_or_b64 vcc, vcc, s[0:1]
	v_cndmask_b32_e32 v65, v65, v219, vcc
	v_cmp_lt_i32_e32 vcc, 6, v68
	v_cmp_gt_i32_e64 s[0:1], 6, v69
	s_or_b64 vcc, vcc, s[0:1]
	v_max3_f32 v72, v70, s41, v71
	v_cndmask_b32_e32 v66, v66, v219, vcc
	v_cmp_lt_i32_e32 vcc, 7, v68
	v_cmp_gt_i32_e64 s[0:1], 7, v69
	v_max3_f32 v72, v72, v73, v74
	s_or_b64 vcc, vcc, s[0:1]
	v_max3_f32 v72, v72, v64, v65
	v_cndmask_b32_e32 v67, v67, v219, vcc
	v_max3_f32 v68, v72, v66, v67
	v_mov_b32_e32 v69, v68
	v_mov_b32_e32 v245, v68
	s_nop 1
	v_permlane16_swap_b32_e32 v69, v245
	v_max_f32_e32 v69, v69, v245
	s_min_i32 s0, s22, 35
	s_add_i32 s0, s0, -16
	s_ashr_i32 s1, s0, 31
	s_lshr_b32 s1, s1, 30
	s_waitcnt lgkmcnt(0)
	v_max_f32_e32 v69, v69, v69
	v_max_f32_e32 v68, v68, v69
	v_mov_b32_e32 v69, v68
	v_mov_b32_e32 v245, v68
	s_nop 1
	v_permlane32_swap_b32_e32 v69, v245
	v_max_f32_e32 v69, v69, v245
	s_add_i32 s1, s0, s1
	s_ashr_i32 s23, s1, 2
	s_and_b32 s1, s1, 0x3ffffffc
	s_sub_i32 s0, s0, s1
	s_waitcnt lgkmcnt(0)
	v_max3_f32 v144, v236, v68, v69
	s_lshl_b32 s0, s0, 2
	v_sub_f32_e32 v69, v70, v144
	v_sub_f32_e32 v64, v64, v144
	s_add_i32 s24, s23, 18
	s_add_i32 s0, s0, s42
	v_exp_f32_e32 v163, v69
	v_sub_f32_e32 v69, v71, v144
	v_exp_f32_e32 v171, v64
	v_sub_f32_e32 v64, v65, v144
	s_cmp_gt_u32 s23, 0xffffffed
	v_exp_f32_e32 v165, v69
	v_sub_f32_e32 v69, v73, v144
	v_exp_f32_e32 v173, v64
	v_sub_f32_e32 v64, v66, v144
	s_cselect_b64 vcc, -1, 0
	s_lshl_b32 s1, s24, 3
	v_exp_f32_e32 v167, v69
	v_sub_f32_e32 v69, v74, v144
	v_exp_f32_e32 v175, v64
	v_sub_f32_e32 v64, v67, v144
	s_add_i32 s1, s1, s47
	s_lshl_b32 s23, s24, 5
	v_exp_f32_e32 v169, v69
	v_exp_f32_e32 v177, v64
	v_add_u32_e32 v64, s23, v231
	v_mov_b32_e32 v69, s1
	v_cndmask_b32_e32 v64, v64, v69, vcc
	v_sub_f32_e32 v68, v236, v144
	v_add_u32_e32 v64, v64, v227
	v_exp_f32_e32 v179, v68
	v_mov_b32_e32 v68, s0
	v_max_i32_e32 v65, 0, v64
	v_max_i32_e32 v64, -4, v64
	v_cndmask_b32_e32 v66, v68, v229, vcc
	v_min_i32_e32 v65, s43, v65
	v_add_u32_e32 v64, 4, v64
	v_min_u32_e32 v67, s43, v64
	v_lshl_add_u32 v64, v65, 4, v66
	v_ashrrev_i32_e32 v65, 31, v64
	v_lshl_add_u32 v66, v67, 4, v66
	v_lshrrev_b32_e32 v243, 8, v64
	v_and_b32_e32 v244, 15, v64
	v_lshlrev_b32_e32 v243, 18, v243
	v_lshl_or_b32 v243, v244, 11, v243
	v_bfe_u32 v244, v64, 6, 2
	v_lshl_or_b32 v243, v244, 9, v243
	v_bfe_u32 v244, v64, 4, 2
	v_lshl_or_b32 v64, v244, 5, v243
	v_mov_b32_e32 v65, 0
	v_ashrrev_i32_e32 v67, 31, v66
	v_lshl_add_u64 v[64:65], v[154:155], 0, v[64:65]
; __device__ __forceinline__ KVB attn_load(int ks, const u16* __restrict__ kbase, const u16* __restrict__ vbase, int L16,
;                                          int r, int i0, int lane) {
;   KVB b;
;   const int quad = lane >> 4, l15 = lane & 15, gk = l15 >> 2, ek = l15 & 3;
;   int cK, sK; attn_desc(ks, gk, r, i0, cK, sK);
;   int ia = sK + ek, ib = ia + 4;
;   ia = min(max(ia, 0), L16 - 1); ib = min(max(ib, 0), L16 - 1);
;   const u16* ka = kbase + (size_t)(cK + 16 * ia) * 512;
; __device__ __forceinline__ void attn_step(int ks, const KVB& b, int L16, int r, int i0, int iq, int lane,
;                                           const bf16x8* qs, f32x4 (&o)[4], float& mrun, float& lrun) {
;     ...
;   f32x4 sa = __builtin_amdgcn_mfma_f32_16x16x32_bf16(b.k0, qB0, z, 0, 0, 0);
;   sa = __builtin_amdgcn_mfma_f32_16x16x32_bf16(b.k1, qB1, sa, 0, 0, 0);
;   f32x4 sb = __builtin_amdgcn_mfma_f32_16x16x32_bf16(b.k2, qB0, z, 0, 0, 0);
;   sb = __builtin_amdgcn_mfma_f32_16x16x32_bf16(b.k3, qB1, sb, 0, 0, 0);
;   int jlo = max(iq - D + (cV < r ? 1 : 0), 0) - sV;
;   int jhi = min(iq + D - (cV > r ? 1 : 0), L16 - 1) - sV;
;   const float NINF = -__builtin_inff();
;   float s8[8];
;   float mt = -1e30f;
; #pragma unroll
;   for (int j = 0; j < 8; ++j) {
;     float sv = j < 4 ? sa[j] : sb[j - 4];
;     sv = (j >= jlo && j <= jhi) ? sv : NINF;
;     s8[j] = sv;
;     mt = fmaxf(mt, sv);
;   }
;   mt = fmaxf(mt, __shfl_xor(mt, 16));
;   mt = fmaxf(mt, __shfl_xor(mt, 32));
;   float mnew = fmaxf(mrun, mt);
;   float alpha = __builtin_amdgcn_exp2f(mrun - mnew);
;   mrun = mnew;
;   float ps = 0.f;
;   float p8[8];
; #pragma unroll
;   for (int j = 0; j < 8; ++j) { p8[j] = __builtin_amdgcn_exp2f(s8[j] - mnew); ps += p8[j]; }
;   lrun = lrun * alpha + ps;
;   union { uint4 u; bf16x8 v; } pb;
;   pb.u = make_uint4(pack2(p8[0], p8[1]), pack2(p8[2], p8[3]), pack2(p8[4], p8[5]), pack2(p8[6], p8[7]));
; #pragma unroll
;   for (int dt = 0; dt < 4; ++dt) { o[dt][0] *= alpha; o[dt][1] *= alpha; o[dt][2] *= alpha; o[dt][3] *= alpha; }
;   o[0] = __builtin_amdgcn_mfma_f32_16x16x32_bf16(b.v0, pb.v, o[0], 0, 0, 0);
;   o[1] = __builtin_amdgcn_mfma_f32_16x16x32_bf16(b.v1, pb.v, o[1], 0, 0, 0);
;   o[2] = __builtin_amdgcn_mfma_f32_16x16x32_bf16(b.v2, pb.v, o[2], 0, 0, 0);
;   o[3] = __builtin_amdgcn_mfma_f32_16x16x32_bf16(b.v3, pb.v, o[3], 0, 0, 0);
	v_lshrrev_b32_e32 v243, 8, v66
	v_and_b32_e32 v244, 15, v66
	v_lshlrev_b32_e32 v243, 18, v243
	v_lshl_or_b32 v243, v244, 11, v243
	v_bfe_u32 v244, v66, 6, 2
	v_lshl_or_b32 v243, v244, 9, v243
	v_bfe_u32 v244, v66, 4, 2
	v_lshl_or_b32 v66, v244, 5, v243
	v_mov_b32_e32 v67, 0
	v_lshl_add_u64 v[66:67], v[154:155], 0, v[66:67]
	global_load_dwordx4 v[124:127], v[64:65], off
	global_load_dwordx4 v[120:123], v[64:65], off offset:16
	global_load_dwordx4 v[116:119], v[66:67], off
	global_load_dwordx4 v[112:115], v[66:67], off offset:16
	v_add_u32_e32 v65, s23, v232
	v_cndmask_b32_e32 v64, v68, v230, vcc
	v_cndmask_b32_e32 v66, v65, v69, vcc
	v_ashrrev_i32_e32 v65, 31, v64
	v_ashrrev_i32_e32 v66, 2, v66
	v_lshlrev_b64 v[64:65], s44, v[64:65]
	v_ashrrev_i32_e32 v67, 31, v66
	v_lshl_add_u64 v[64:65], v[64:65], 0, v[66:67]
	v_lshlrev_b64 v[64:65], 9, v[64:65]
	v_lshl_add_u64 v[78:79], v[158:159], 0, v[64:65]
	s_mov_b32 s0, s10
	s_mov_b32 s1, s46
	global_load_dwordx2 v[64:65], v[78:79], off
	global_load_dwordx2 v[66:67], v[78:79], off offset:512
	global_load_dwordx2 v[68:69], v[78:79], off offset:128
	global_load_dwordx2 v[70:71], v[78:79], off offset:640
	global_load_dwordx2 v[72:73], v[78:79], off offset:256
	global_load_dwordx2 v[74:75], v[78:79], off offset:768
	global_load_dwordx2 v[76:77], v[78:79], off offset:384
	s_nop 0
	global_load_dwordx2 v[78:79], v[78:79], off offset:896
	ds_read_b128 v[184:187], v228 offset:6144
	ds_read_b128 v[188:191], v228 offset:7168
	s_waitcnt vmcnt(23) lgkmcnt(1)
	v_mfma_f32_16x16x32_bf16 v[96:99], v[96:99], v[184:187], 0
	v_ashrrev_i32_e32 v162, 4, v162
	s_sub_i32 s0, s1, 64
	v_add_u32_e32 v162, s11, v162
	s_waitcnt vmcnt(22) lgkmcnt(0)
	v_mfma_f32_16x16x32_bf16 v[96:99], v[100:103], v[188:191], v[96:99]
	v_lshl_add_u32 v162, v162, 3, s0
	v_mov_b32_e32 v236, v144
	s_waitcnt vmcnt(21)
	v_mfma_f32_16x16x32_bf16 v[100:103], v[104:107], v[184:187], 0
	v_subrev_u32_e32 v104, 64, v164
	v_add_u32_e32 v105, 64, v164
	v_max_i32_e32 v104, 0, v104
	v_min_i32_e32 v105, s43, v105
	v_sub_u32_e32 v104, v104, v162
	v_sub_u32_e32 v105, v105, v162
	v_cmp_lt_i32_e32 vcc, 0, v104
	v_cmp_gt_i32_e64 s[0:1], 0, v105
	s_or_b64 vcc, vcc, s[0:1]
	v_cndmask_b32_e32 v96, v96, v219, vcc
	v_cmp_lt_i32_e32 vcc, 1, v104
	v_cmp_gt_i32_e64 s[0:1], 1, v105
	s_or_b64 vcc, vcc, s[0:1]
	v_cndmask_b32_e32 v97, v97, v219, vcc
	v_cmp_lt_i32_e32 vcc, 2, v104
	v_cmp_gt_i32_e64 s[0:1], 2, v105
	s_or_b64 vcc, vcc, s[0:1]
	s_waitcnt vmcnt(20)
	v_mfma_f32_16x16x32_bf16 v[100:103], v[108:111], v[188:191], v[100:103]
	v_cndmask_b32_e32 v98, v98, v219, vcc
	v_cmp_lt_i32_e32 vcc, 3, v104
	v_cmp_gt_i32_e64 s[0:1], 3, v105
	s_or_b64 vcc, vcc, s[0:1]
	v_cndmask_b32_e32 v99, v99, v219, vcc
	v_cmp_lt_i32_e32 vcc, 4, v104
	v_cmp_gt_i32_e64 s[0:1], 4, v105
	s_or_b64 vcc, vcc, s[0:1]
	v_cndmask_b32_e32 v100, v100, v219, vcc
	v_cmp_lt_i32_e32 vcc, 5, v104
	v_cmp_gt_i32_e64 s[0:1], 5, v105
	s_or_b64 vcc, vcc, s[0:1]
	v_cndmask_b32_e32 v101, v101, v219, vcc
	v_cmp_lt_i32_e32 vcc, 6, v104
	v_cmp_gt_i32_e64 s[0:1], 6, v105
	s_or_b64 vcc, vcc, s[0:1]
	v_max3_f32 v106, v96, s41, v97
	v_cndmask_b32_e32 v102, v102, v219, vcc
	v_cmp_lt_i32_e32 vcc, 7, v104
	v_cmp_gt_i32_e64 s[0:1], 7, v105
	v_max3_f32 v106, v106, v98, v99
	s_or_b64 vcc, vcc, s[0:1]
	v_max3_f32 v106, v106, v100, v101
	v_cndmask_b32_e32 v103, v103, v219, vcc
	v_max3_f32 v104, v106, v102, v103
	v_mov_b32_e32 v105, v104
	v_mov_b32_e32 v245, v104
	s_nop 1
	v_permlane16_swap_b32_e32 v105, v245
	v_max_f32_e32 v105, v105, v245
	s_min_i32 s0, s22, 34
	s_add_i32 s0, s0, -15
	s_ashr_i32 s1, s0, 31
	s_lshr_b32 s1, s1, 30
	s_waitcnt lgkmcnt(0)
	v_max_f32_e32 v105, v105, v105
	v_max_f32_e32 v104, v104, v105
	v_mov_b32_e32 v105, v104
	v_mov_b32_e32 v245, v104
	s_nop 1
	v_permlane32_swap_b32_e32 v105, v245
	v_max_f32_e32 v105, v105, v245
	s_add_i32 s1, s0, s1
	s_ashr_i32 s22, s1, 2
	s_and_b32 s1, s1, 0x3ffffffc
	s_sub_i32 s0, s0, s1
	s_waitcnt lgkmcnt(0)
	v_max3_f32 v184, v235, v104, v105
	v_sub_f32_e32 v96, v96, v184
	v_exp_f32_e32 v162, v96
	v_sub_f32_e32 v96, v97, v184
	v_exp_f32_e32 v164, v96
	v_sub_f32_e32 v96, v98, v184
	v_exp_f32_e32 v166, v96
	v_sub_f32_e32 v96, v99, v184
	v_exp_f32_e32 v168, v96
	v_sub_f32_e32 v96, v100, v184
	v_exp_f32_e32 v170, v96
	v_sub_f32_e32 v96, v101, v184
	v_exp_f32_e32 v172, v96
	v_sub_f32_e32 v96, v102, v184
	v_exp_f32_e32 v174, v96
	v_sub_f32_e32 v96, v103, v184
	v_exp_f32_e32 v176, v96
	v_pk_add_f32 v[96:97], v[162:163], 0 op_sel_hi:[1,0]
	v_sub_f32_e32 v104, v235, v184
	v_pk_add_f32 v[96:97], v[164:165], v[96:97]
	v_exp_f32_e32 v178, v104
	v_pk_add_f32 v[96:97], v[166:167], v[96:97]
	s_lshl_b32 s0, s0, 2
	v_pk_add_f32 v[96:97], v[168:169], v[96:97]
	s_add_i32 s23, s22, 18
	v_pk_add_f32 v[96:97], v[170:171], v[96:97]
	s_add_i32 s0, s0, s42
	v_pk_add_f32 v[96:97], v[172:173], v[96:97]
	s_cmp_gt_u32 s22, 0xffffffed
	v_pk_add_f32 v[96:97], v[174:175], v[96:97]
	v_cvt_pk_bf16_f32 v98, v171, v173
	v_pk_add_f32 v[100:101], v[176:177], v[96:97]
	v_mov_b32_e32 v96, v179
	v_pk_mul_f32 v[34:35], v[34:35], v[96:97] op_sel_hi:[1,0]
	v_pk_mul_f32 v[32:33], v[32:33], v[96:97] op_sel_hi:[1,0]
	v_pk_mul_f32 v[26:27], v[26:27], v[96:97] op_sel_hi:[1,0]
	v_pk_mul_f32 v[24:25], v[24:25], v[96:97] op_sel_hi:[1,0]
	v_pk_mul_f32 v[22:23], v[22:23], v[96:97] op_sel_hi:[1,0]
	v_pk_mul_f32 v[20:21], v[20:21], v[96:97] op_sel_hi:[1,0]
	v_pk_mul_f32 v[14:15], v[14:15], v[96:97] op_sel_hi:[1,0]
	v_pk_mul_f32 v[12:13], v[12:13], v[96:97] op_sel_hi:[1,0]
	v_cvt_pk_bf16_f32 v96, v163, v165
	v_cvt_pk_bf16_f32 v97, v167, v169
	v_cvt_pk_bf16_f32 v99, v175, v177
	s_cselect_b64 vcc, -1, 0
	s_lshl_b32 s1, s23, 3
	v_mfma_f32_16x16x32_bf16 v[32:35], v[128:131], v[96:99], v[32:35]
	v_mul_f32_e64 v18, v18, v178
	v_mul_f32_e64 v19, v19, v178
	v_pk_mul_f32 v[16:17], v[16:17], v[178:179] op_sel_hi:[1,0]
	v_pk_mul_f32 v[10:11], v[10:11], v[178:179] op_sel_hi:[1,0]
	v_mfma_f32_16x16x32_bf16 v[24:27], v[132:135], v[96:99], v[24:27]
	v_mul_f32_e64 v8, v8, v178
	v_mul_f32_e64 v9, v9, v178
	s_add_i32 s1, s1, s47
	s_lshl_b32 s22, s23, 5
	v_mfma_f32_16x16x32_bf16 v[20:23], v[136:139], v[96:99], v[20:23]
	v_mul_f32_e64 v6, v6, v178
	v_mul_f32_e64 v7, v7, v178
	v_pk_mul_f32 v[4:5], v[4:5], v[178:179] op_sel_hi:[1,0]
	v_pk_mul_f32 v[2:3], v[2:3], v[178:179] op_sel_hi:[1,0]
	v_mfma_f32_16x16x32_bf16 v[12:15], v[140:143], v[96:99], v[12:15]
	v_cvt_pk_bf16_f32 v96, v162, v164
	v_cvt_pk_bf16_f32 v97, v166, v168
	v_cvt_pk_bf16_f32 v98, v170, v172
	v_cvt_pk_bf16_f32 v99, v174, v176
	v_pk_mul_f32 v[0:1], v[0:1], v[178:179] op_sel_hi:[1,0]
	v_pk_fma_f32 v[156:157], v[156:157], v[178:179], v[100:101]
	s_waitcnt vmcnt(18)
; __device__ __forceinline__ KVB attn_load(int ks, const u16* __restrict__ kbase, const u16* __restrict__ vbase, int L16,
;                                          int r, int i0, int lane) {
;   KVB b;
;   const int quad = lane >> 4, l15 = lane & 15, gk = l15 >> 2, ek = l15 & 3;
;   int cK, sK; attn_desc(ks, gk, r, i0, cK, sK);
;   int ia = sK + ek, ib = ia + 4;
;   ia = min(max(ia, 0), L16 - 1); ib = min(max(ib, 0), L16 - 1);
;   const u16* ka = kbase + (size_t)(cK + 16 * ia) * 512;
;   const u16* kb = kbase + (size_t)(cK + 16 * ib) * 512;
;   b.k0 = *(const bf16x8*)ka; b.k1 = *(const bf16x8*)(ka + 8);
;   b.k2 = *(const bf16x8*)kb; b.k3 = *(const bf16x8*)(kb + 8);
;   int cV, sV; attn_desc(ks, quad, r, i0, cV, sV);
;   const u16* vp = vbase + ((ptrdiff_t)cV * (L16 >> 2) + (sV >> 2)) * 256 + l15 * 4;
;   {
;     union { struct { uint2 a, b; } p; bf16x8 v; } c0, c1, c2, c3;
;     c0.p.a = *(const uint2*)(vp);        c0.p.b = *(const uint2*)(vp + 256);
;     c1.p.a = *(const uint2*)(vp + 64);   c1.p.b = *(const uint2*)(vp + 64 + 256);
;     c2.p.a = *(const uint2*)(vp + 128);  c2.p.b = *(const uint2*)(vp + 128 + 256);
;     c3.p.a = *(const uint2*)(vp + 192);  c3.p.b = *(const uint2*)(vp + 192 + 256);
;     b.v0 = c0.v; b.v1 = c1.v; b.v2 = c2.v; b.v3 = c3.v;
;   }
;   return b;
; template <int NT>
; __device__ void attn_unitN(const P& p, int u) {
;     ...
;   for (int kk = 0; kk < 5; ++kk) {
;     int e0 = 18 + NT * kk, ks = 18 + kk;
; #pragma unroll
;     for (int t = 0; t < NT; t += 2) {
;       attn_step(ks, bA, L16, rb + RS * t, i0, iq, lane, qs + t * 128, o[t], mrun[t], lrun[t]);
;       { int f = min(e0 + t + 2, EMAX) - 18;
;         bA = attn_load(18 + f / NT, kbase, vbase, L16, rb + RS * (f % NT), i0, lane); }
;       attn_step(ks, bB, L16, rb + RS * (t + 1), i0, iq, lane, qs + (t + 1) * 128, o[t + 1], mrun[t + 1], lrun[t + 1]);
;       { int f = min(e0 + t + 3, EMAX) - 18;
;         bB = attn_load(18 + f / NT, kbase, vbase, L16, rb + RS * (f % NT), i0, lane); }
;     }
	v_mfma_f32_16x16x32_bf16 v[16:19], v[80:83], v[96:99], v[16:19]
	v_add_u32_e32 v80, s22, v231
	s_add_i32 s11, s11, 4
	s_cmp_lg_u32 s11, 20
	s_waitcnt vmcnt(16)
	v_mfma_f32_16x16x32_bf16 v[8:11], v[84:87], v[96:99], v[8:11]
	v_mov_b32_e32 v85, s1
	v_cndmask_b32_e32 v80, v80, v85, vcc
	v_add_u32_e32 v80, v80, v227
	v_mov_b32_e32 v84, s0
	v_max_i32_e32 v81, 0, v80
	v_max_i32_e32 v80, -4, v80
	v_cndmask_b32_e32 v82, v84, v229, vcc
	v_min_i32_e32 v81, s43, v81
	v_add_u32_e32 v80, 4, v80
	v_min_u32_e32 v83, s43, v80
	v_lshl_add_u32 v80, v81, 4, v82
	v_ashrrev_i32_e32 v81, 31, v80
	v_lshl_add_u32 v82, v83, 4, v82
	v_lshrrev_b32_e32 v243, 8, v80
	v_and_b32_e32 v244, 15, v80
	v_lshlrev_b32_e32 v243, 18, v243
	v_lshl_or_b32 v243, v244, 11, v243
	v_bfe_u32 v244, v80, 6, 2
	v_lshl_or_b32 v243, v244, 9, v243
	v_bfe_u32 v244, v80, 4, 2
	v_lshl_or_b32 v80, v244, 5, v243
	v_mov_b32_e32 v81, 0
	v_ashrrev_i32_e32 v83, 31, v82
	v_lshl_add_u64 v[80:81], v[154:155], 0, v[80:81]
	v_lshrrev_b32_e32 v243, 8, v82
	v_and_b32_e32 v244, 15, v82
	v_lshlrev_b32_e32 v243, 18, v243
	v_lshl_or_b32 v243, v244, 11, v243
	v_bfe_u32 v244, v82, 6, 2
	v_lshl_or_b32 v243, v244, 9, v243
	v_bfe_u32 v244, v82, 4, 2
	v_lshl_or_b32 v82, v244, 5, v243
	v_mov_b32_e32 v83, 0
	s_waitcnt vmcnt(14)
	v_mfma_f32_16x16x32_bf16 v[4:7], v[88:91], v[96:99], v[4:7]
	v_lshl_add_u64 v[82:83], v[154:155], 0, v[82:83]
	v_mov_b32_e32 v235, v184
	v_mov_b32_e32 v143, v182
	s_waitcnt vmcnt(12)
	v_mfma_f32_16x16x32_bf16 v[0:3], v[92:95], v[96:99], v[0:3]
	global_load_dwordx4 v[108:111], v[80:81], off
	global_load_dwordx4 v[104:107], v[80:81], off offset:16
	global_load_dwordx4 v[100:103], v[82:83], off
	global_load_dwordx4 v[96:99], v[82:83], off offset:16
	v_add_u32_e32 v81, s22, v232
	v_cndmask_b32_e32 v80, v84, v230, vcc
	v_cndmask_b32_e32 v82, v81, v85, vcc
	v_ashrrev_i32_e32 v81, 31, v80
	v_ashrrev_i32_e32 v82, 2, v82
	v_lshlrev_b64 v[80:81], s44, v[80:81]
	v_ashrrev_i32_e32 v83, 31, v82
	v_lshl_add_u64 v[80:81], v[80:81], 0, v[82:83]
	v_lshlrev_b64 v[80:81], 9, v[80:81]
	v_lshl_add_u64 v[94:95], v[158:159], 0, v[80:81]
	global_load_dwordx2 v[80:81], v[94:95], off
	global_load_dwordx2 v[82:83], v[94:95], off offset:512
	global_load_dwordx2 v[84:85], v[94:95], off offset:128
	global_load_dwordx2 v[86:87], v[94:95], off offset:640
	global_load_dwordx2 v[88:89], v[94:95], off offset:256
	global_load_dwordx2 v[90:91], v[94:95], off offset:768
	global_load_dwordx2 v[92:93], v[94:95], off offset:384
	s_nop 0
	global_load_dwordx2 v[94:95], v[94:95], off offset:896
	s_cbranch_scc1 .LBB0_267
; template <int NT>
; __device__ void attn_unitN(const P& p, int u) {
;     ...
;   u16* omix = (u16*)(p.ws + OFF_OMIX);
; #pragma unroll
;   for (int t = 0; t < NT; ++t) {
;     float l = lrun[t];
;     l += __shfl_xor(l, 16);
;     l += __shfl_xor(l, 32);
;     float inv = 1.f / l;
;     u16* op = omix + (size_t)(seq0 + rb + RS * t + 16 * iq) * 1024 + h * 64 + quad * 4;
; #pragma unroll
;     for (int dt = 0; dt < 4; ++dt) {
;       uint2 w; w.x = pack2(o[t][dt][0] * inv, o[t][dt][1] * inv); w.y = pack2(o[t][dt][2] * inv, o[t][dt][3] * inv);
;       *(uint2*)(op + dt * 16) = w;
;     }
;   }
	s_waitcnt vmcnt(19)
	ds_bpermute_b32 v64, v233, v161
	s_lshl_b32 s0, s45, 1
	s_waitcnt vmcnt(18)
	v_lshrrev_b32_e32 v66, 1, v224
	s_add_u32 s0, s34, s0
	v_and_b32_e32 v144, 24, v66
	s_waitcnt lgkmcnt(0)
	v_add_f32_e32 v67, v161, v64
	s_waitcnt vmcnt(17)
	ds_bpermute_b32 v68, v234, v67
	s_addc_u32 s1, s35, 0
	v_lshlrev_b64 v[64:65], 11, v[152:153]
	s_add_i32 s3, s3, s30
	s_cmpk_lt_i32 s3, 0x2000
	s_waitcnt lgkmcnt(0)
	v_add_f32_e32 v68, v67, v68
	v_div_scale_f32 v69, s[4:5], v68, v68, 1.0
	s_waitcnt vmcnt(16)
	v_rcp_f32_e32 v70, v69
	v_div_scale_f32 v71, vcc, 1.0, v68, 1.0
	v_lshl_add_u64 v[66:67], s[0:1], 0, v[144:145]
	s_waitcnt vmcnt(15)
	v_fma_f32 v72, -v69, v70, 1.0
	v_fmac_f32_e32 v70, v72, v70
	v_mul_f32_e32 v72, v71, v70
	v_fma_f32 v73, -v69, v72, v71
	v_fmac_f32_e32 v72, v73, v70
	v_fma_f32 v69, -v69, v72, v71
	v_div_fmas_f32 v69, v69, v70, v72
	v_div_fixup_f32 v68, v69, v68, 1.0
	v_pk_mul_f32 v[56:57], v[56:57], v[68:69] op_sel_hi:[1,0]
	v_pk_mul_f32 v[58:59], v[58:59], v[68:69] op_sel_hi:[1,0]
	v_cvt_pk_bf16_f32 v56, v56, v57
	v_cvt_pk_bf16_f32 v57, v58, v59
	ds_bpermute_b32 v58, v233, v160
	v_lshl_add_u64 v[64:65], v[66:67], 0, v[64:65]
	global_store_dwordx2 v[64:65], v[56:57], off offset:32
	v_pk_mul_f32 v[52:53], v[52:53], v[68:69] op_sel_hi:[1,0]
	v_pk_mul_f32 v[54:55], v[54:55], v[68:69] op_sel_hi:[1,0]
	s_waitcnt lgkmcnt(0)
	v_add_f32_e32 v56, v160, v58
	ds_bpermute_b32 v57, v234, v56
	v_cvt_pk_bf16_f32 v52, v52, v53
	v_cvt_pk_bf16_f32 v53, v54, v55
	global_store_dwordx2 v[64:65], v[52:53], off offset:64
	v_pk_mul_f32 v[44:45], v[44:45], v[68:69] op_sel_hi:[1,0]
	s_waitcnt lgkmcnt(0)
	v_add_f32_e32 v52, v56, v57
	v_div_scale_f32 v53, s[0:1], v52, v52, 1.0
	v_rcp_f32_e32 v54, v53
	v_pk_mul_f32 v[46:47], v[46:47], v[68:69] op_sel_hi:[1,0]
	v_cvt_pk_bf16_f32 v44, v44, v45
	v_cvt_pk_bf16_f32 v45, v46, v47
	global_store_dwordx2 v[64:65], v[44:45], off offset:96
	v_fma_f32 v44, -v53, v54, 1.0
	v_fmac_f32_e32 v54, v44, v54
	v_div_scale_f32 v44, vcc, 1.0, v52, 1.0
	v_mul_f32_e32 v45, v44, v54
	v_fma_f32 v46, -v53, v45, v44
	v_fmac_f32_e32 v45, v46, v54
	v_fma_f32 v44, -v53, v45, v44
	v_div_fmas_f32 v44, v44, v54, v45
	v_div_fixup_f32 v44, v44, v52, 1.0
	v_pk_mul_f32 v[40:41], v[40:41], v[44:45] op_sel_hi:[1,0]
	v_pk_mul_f32 v[42:43], v[42:43], v[44:45] op_sel_hi:[1,0]
	v_cvt_pk_bf16_f32 v40, v40, v41
	v_cvt_pk_bf16_f32 v41, v42, v43
	ds_bpermute_b32 v42, v233, v157
	v_lshlrev_b64 v[46:47], 11, v[150:151]
	v_lshl_add_u64 v[46:47], v[66:67], 0, v[46:47]
	global_store_dwordx2 v[46:47], v[40:41], off offset:32
	v_pk_mul_f32 v[36:37], v[36:37], v[44:45] op_sel_hi:[1,0]
	s_waitcnt lgkmcnt(0)
	v_add_f32_e32 v40, v157, v42
	ds_bpermute_b32 v41, v234, v40
	v_pk_mul_f32 v[38:39], v[38:39], v[44:45] op_sel_hi:[1,0]
	v_cvt_pk_bf16_f32 v36, v36, v37
	v_cvt_pk_bf16_f32 v37, v38, v39
	global_store_dwordx2 v[46:47], v[36:37], off offset:64
	s_waitcnt lgkmcnt(0)
	v_add_f32_e32 v36, v40, v41
	v_div_scale_f32 v37, s[0:1], v36, v36, 1.0
	v_rcp_f32_e32 v38, v37
	v_pk_mul_f32 v[28:29], v[28:29], v[44:45] op_sel_hi:[1,0]
	v_pk_mul_f32 v[30:31], v[30:31], v[44:45] op_sel_hi:[1,0]
	v_cvt_pk_bf16_f32 v28, v28, v29
	v_cvt_pk_bf16_f32 v29, v30, v31
	global_store_dwordx2 v[46:47], v[28:29], off offset:96
	v_fma_f32 v28, -v37, v38, 1.0
	v_fmac_f32_e32 v38, v28, v38
	v_div_scale_f32 v28, vcc, 1.0, v36, 1.0
	v_mul_f32_e32 v29, v28, v38
	v_fma_f32 v30, -v37, v29, v28
	v_fmac_f32_e32 v29, v30, v38
	v_fma_f32 v28, -v37, v29, v28
	v_div_fmas_f32 v28, v28, v38, v29
	v_div_fixup_f32 v28, v28, v36, 1.0
	v_pk_mul_f32 v[24:25], v[24:25], v[28:29] op_sel_hi:[1,0]
	v_pk_mul_f32 v[26:27], v[26:27], v[28:29] op_sel_hi:[1,0]
	v_cvt_pk_bf16_f32 v24, v24, v25
	v_cvt_pk_bf16_f32 v25, v26, v27
	ds_bpermute_b32 v26, v233, v156
	v_lshlrev_b64 v[30:31], 11, v[148:149]
	v_lshl_add_u64 v[30:31], v[66:67], 0, v[30:31]
	global_store_dwordx2 v[30:31], v[24:25], off offset:32
	v_pk_mul_f32 v[20:21], v[20:21], v[28:29] op_sel_hi:[1,0]
	s_waitcnt lgkmcnt(0)
	v_add_f32_e32 v24, v156, v26
	ds_bpermute_b32 v25, v234, v24
	v_pk_mul_f32 v[22:23], v[22:23], v[28:29] op_sel_hi:[1,0]
	v_cvt_pk_bf16_f32 v20, v20, v21
	v_cvt_pk_bf16_f32 v21, v22, v23
	global_store_dwordx2 v[30:31], v[20:21], off offset:64
	s_waitcnt lgkmcnt(0)
	v_add_f32_e32 v20, v24, v25
	v_div_scale_f32 v21, s[0:1], v20, v20, 1.0
	v_rcp_f32_e32 v22, v21
	v_pk_mul_f32 v[12:13], v[12:13], v[28:29] op_sel_hi:[1,0]
	v_pk_mul_f32 v[14:15], v[14:15], v[28:29] op_sel_hi:[1,0]
	v_cvt_pk_bf16_f32 v12, v12, v13
	v_cvt_pk_bf16_f32 v13, v14, v15
	global_store_dwordx2 v[30:31], v[12:13], off offset:96
	v_fma_f32 v12, -v21, v22, 1.0
	v_fmac_f32_e32 v22, v12, v22
	v_div_scale_f32 v12, vcc, 1.0, v20, 1.0
	v_mul_f32_e32 v13, v12, v22
	v_fma_f32 v14, -v21, v13, v12
	v_fmac_f32_e32 v13, v14, v22
	v_fma_f32 v12, -v21, v13, v12
	v_div_fmas_f32 v12, v12, v22, v13
	v_div_fixup_f32 v12, v12, v20, 1.0
	v_pk_mul_f32 v[60:61], v[60:61], v[68:69] op_sel_hi:[1,0]
	v_pk_mul_f32 v[62:63], v[62:63], v[68:69] op_sel_hi:[1,0]
	v_pk_mul_f32 v[48:49], v[48:49], v[44:45] op_sel_hi:[1,0]
	v_pk_mul_f32 v[50:51], v[50:51], v[44:45] op_sel_hi:[1,0]
	v_pk_mul_f32 v[32:33], v[32:33], v[28:29] op_sel_hi:[1,0]
	v_pk_mul_f32 v[34:35], v[34:35], v[28:29] op_sel_hi:[1,0]
	v_lshlrev_b64 v[14:15], 11, v[146:147]
	v_pk_mul_f32 v[16:17], v[16:17], v[12:13] op_sel_hi:[1,0]
	v_pk_mul_f32 v[18:19], v[18:19], v[12:13] op_sel_hi:[1,0]
	v_pk_mul_f32 v[8:9], v[8:9], v[12:13] op_sel_hi:[1,0]
	v_pk_mul_f32 v[10:11], v[10:11], v[12:13] op_sel_hi:[1,0]
	v_pk_mul_f32 v[4:5], v[4:5], v[12:13] op_sel_hi:[1,0]
	v_pk_mul_f32 v[6:7], v[6:7], v[12:13] op_sel_hi:[1,0]
	v_pk_mul_f32 v[0:1], v[0:1], v[12:13] op_sel_hi:[1,0]
	v_pk_mul_f32 v[2:3], v[2:3], v[12:13] op_sel_hi:[1,0]
	v_cvt_pk_bf16_f32 v60, v60, v61
	v_cvt_pk_bf16_f32 v61, v62, v63
	v_cvt_pk_bf16_f32 v48, v48, v49
	v_cvt_pk_bf16_f32 v49, v50, v51
	v_cvt_pk_bf16_f32 v32, v32, v33
	v_cvt_pk_bf16_f32 v33, v34, v35
	v_lshl_add_u64 v[14:15], v[66:67], 0, v[14:15]
	v_cvt_pk_bf16_f32 v16, v16, v17
	v_cvt_pk_bf16_f32 v17, v18, v19
	v_cvt_pk_bf16_f32 v8, v8, v9
	v_cvt_pk_bf16_f32 v9, v10, v11
	v_cvt_pk_bf16_f32 v4, v4, v5
	v_cvt_pk_bf16_f32 v5, v6, v7
	v_cvt_pk_bf16_f32 v0, v0, v1
	v_cvt_pk_bf16_f32 v1, v2, v3
	global_store_dwordx2 v[64:65], v[60:61], off
	global_store_dwordx2 v[46:47], v[48:49], off
	global_store_dwordx2 v[30:31], v[32:33], off
	global_store_dwordx2 v[14:15], v[16:17], off
	global_store_dwordx2 v[14:15], v[8:9], off offset:32
	global_store_dwordx2 v[14:15], v[4:5], off offset:64
	global_store_dwordx2 v[14:15], v[0:1], off offset:96
	s_cbranch_scc1 .LBB0_231
